# hand-written attention phase: swapped QK^T, P in registers, bias via MFMA C-input, LDS double buffer
# speedup vs baseline: 1.1091x; 1.0530x over previous
; __device__ __forceinline__ void attn_phase(const Params& P, char* smem_raw) {
;     ...
;   const int tid = VTID, lane = tid & 63, wid = tid >> 6;
;   const u16* QKV = P.zq;
;   const u16* VTX = P.zf;
;   const u16* VTC = reinterpret_cast<const u16*>(P.summ);
;   uint4 kreg[4], vreg[4];
;   bf16x8 qn[2];
;     ...
;   int dco[4][4];
; #pragma unroll
;   for (int reg = 0; reg < 4; ++reg) {
;     const int c = wid * 16 + (lane >> 4) * 4 + reg;
;     const int cs = min(max(c - 8, 0), 48);
; #pragma unroll
;     for (int q4 = 0; q4 < 4; ++q4) {
;       const int kc = q4 * 16 + (lane & 15);
;       dco[reg][q4] = (kc >= cs && kc < cs + 16) ? (kc - c + 15) : 465;
;     }
;   }
.LBB0_1489:
	s_cmp_gt_i32 s34, 12
	s_cselect_b64 s[0:1], -1, 0
	s_cmp_lt_i32 s35, 13
	s_cselect_b64 s[4:5], -1, 0
	s_or_b64 s[0:1], s[0:1], s[4:5]
	s_and_b64 vcc, exec, s[0:1]
	s_cbranch_vccnz .LBB0_1555
	s_waitcnt vmcnt(5)
	v_lshl_add_u32 v109, s2, 1, v153
	s_movk_i32 s0, 0x2000
	v_mov_b32_e32 v0, v153
	v_cmp_gt_i32_e32 vcc, s0, v109
	s_barrier
	s_and_saveexec_b64 s[42:43], vcc
	s_cbranch_execz .LBB0_1501
	v_readlane_b32 s0, v252, 0
	v_readlane_b32 s1, v252, 1
	v_readfirstlane_b32 s3, v153
	s_nop 3
	s_sub_u32 s0, s0, 0x170
	s_subb_u32 s1, s1, 0
	s_load_dwordx2 s[12:13], s[0:1], 0xb8
	s_load_dwordx2 s[8:9], s[0:1], 0x130
	s_load_dwordx4 s[4:7], s[0:1], 0x148
	s_load_dwordx2 s[10:11], s[0:1], 0x158
	s_lshl_b32 s100, s2, 1
	s_add_u32 s3, s100, s3
	s_and_b32 s101, s3, 15
	s_lshl_b32 s3, s3, 8
	s_waitcnt lgkmcnt(0)
	s_lshl_b32 s100, s101, 7
	s_add_u32 s4, s4, s100
	s_addc_u32 s5, s5, 0
	s_add_u32 s10, s10, s100
	s_addc_u32 s11, s11, 0
	s_lshl_b32 s100, s101, 20
	s_add_u32 s6, s6, s100
	s_addc_u32 s7, s7, 0
	s_lshl_b32 s100, s101, 15
	s_add_u32 s8, s8, s100
	s_addc_u32 s9, s9, 0
	s_mul_i32 s100, s101, 0x744
	s_add_u32 s12, s12, s100
	s_addc_u32 s13, s13, 0
	v_and_b32_e32 v112, 0xff, v152
	v_and_b32_e32 v113, 63, v152
	v_bfe_u32 v114, v152, 6, 2
	v_lshrrev_b32_e32 v115, 4, v113
	v_and_b32_e32 v116, 15, v113
	v_mul_u32_u24_e32 v117, 0x12000, v153
	v_add_u32_e32 v117, 16, v117
	v_lshrrev_b32_e32 v118, 2, v116
	v_and_b32_e32 v119, 3, v116
	v_lshl_add_u32 v120, v118, 3, v119
	v_bfe_u32 v121, v116, 1, 1
	v_lshl_add_u32 v121, v118, 1, v121
	v_xor_b32_e32 v121, v115, v121
	v_lshl_add_u32 v122, v120, 7, v117
	v_lshl_add_u32 v144, v121, 4, v122
	v_xor_b32_e32 v121, 4, v121
	v_lshl_add_u32 v145, v121, 4, v122
	v_xor_b32_e32 v123, v115, v119
	v_lshl_add_u32 v124, v116, 8, v117
	v_add_u32_e32 v124, 0x4000, v124
	v_xor_b32_e32 v125, 0, v118
	v_lshl_or_b32 v125, v125, 2, v123
	v_lshl_add_u32 v146, v125, 4, v124
	v_xor_b32_e32 v125, 1, v118
	v_lshl_or_b32 v125, v125, 2, v123
	v_lshl_add_u32 v147, v125, 4, v124
	v_xor_b32_e32 v125, 2, v118
	v_lshl_or_b32 v125, v125, 2, v123
	v_lshl_add_u32 v148, v125, 4, v124
	v_xor_b32_e32 v125, 3, v118
	v_lshl_or_b32 v125, v125, 2, v123
	v_lshl_add_u32 v149, v125, 4, v124
	v_lshrrev_b32_e32 v126, 3, v112
	v_and_b32_e32 v127, 7, v112
	v_bfe_u32 v128, v112, 6, 2
	v_bfe_u32 v125, v112, 4, 1
	v_lshl_add_u32 v128, v128, 1, v125
	v_xor_b32_e32 v128, v127, v128
	v_lshl_add_u32 v125, v126, 7, v117
	v_lshl_add_u32 v150, v128, 4, v125
	v_lshrrev_b32_e32 v129, 4, v112
	v_and_b32_e32 v130, 15, v112
	v_xor_b32_e32 v125, v130, v129
	v_lshl_add_u32 v128, v129, 8, v117
	v_lshl_add_u32 v151, v125, 4, v128
	v_add_u32_e32 v151, 0x4000, v151
	v_mul_u32_u24_e32 v125, 0x1800, v126
	v_lshl_add_u32 v154, v127, 4, v125
	v_add_u32_e32 v155, 0x30000, v154
	v_add_u32_e32 v156, 0x60000, v154
	v_add_u32_e32 v157, 0x90000, v154
	v_lshlrev_b32_e32 v125, 14, v129
	v_lshl_add_u32 v158, v130, 4, v125
	v_add_u32_e32 v159, 0x40000, v158
	v_add_u32_e32 v160, 0x80000, v158
	v_add_u32_e32 v161, 0xc0000, v158
	v_lshlrev_b32_e32 v125, 9, v129
	v_lshl_add_u32 v162, v130, 4, v125
	v_add_u32_e32 v163, 0x2000, v162
	v_add_u32_e32 v164, 0x4000, v162
	v_add_u32_e32 v165, 0x6000, v162
	v_lshl_add_u32 v131, v114, 4, v116
	v_mul_u32_u24_e32 v125, 0x1800, v131
	v_lshl_add_u32 v166, v115, 4, v125
	v_lshlrev_b32_e32 v125, 11, v131
	v_lshl_add_u32 v167, v115, 3, v125
	v_sub_u32_e64 v132, v131, 8 clamp
	v_min_u32_e32 v132, 48, v132
	v_lshlrev_b32_e32 v133, 3, v115
	v_mov_b32_e32 v210, 0x7c
	v_add_u32_e32 v134, 0, v133
	v_sub_u32_e32 v135, v134, v132
	v_cmp_gt_u32_e32 vcc, 16, v135
	v_sub_u32_e32 v136, v134, v131
	v_lshlrev_b32_e32 v136, 2, v136
	v_add_u32_e32 v136, 60, v136
	v_cndmask_b32_e32 v168, v210, v136, vcc
	v_add_u32_e32 v134, 1, v133
	v_sub_u32_e32 v135, v134, v132
	v_cmp_gt_u32_e32 vcc, 16, v135
	v_sub_u32_e32 v136, v134, v131
	v_lshlrev_b32_e32 v136, 2, v136
	v_add_u32_e32 v136, 60, v136
	v_cndmask_b32_e32 v169, v210, v136, vcc
	v_add_u32_e32 v134, 2, v133
	v_sub_u32_e32 v135, v134, v132
	v_cmp_gt_u32_e32 vcc, 16, v135
	v_sub_u32_e32 v136, v134, v131
	v_lshlrev_b32_e32 v136, 2, v136
	v_add_u32_e32 v136, 60, v136
	v_cndmask_b32_e32 v170, v210, v136, vcc
	v_add_u32_e32 v134, 3, v133
	v_sub_u32_e32 v135, v134, v132
	v_cmp_gt_u32_e32 vcc, 16, v135
	v_sub_u32_e32 v136, v134, v131
	v_lshlrev_b32_e32 v136, 2, v136
	v_add_u32_e32 v136, 60, v136
	v_cndmask_b32_e32 v171, v210, v136, vcc
	v_add_u32_e32 v134, 4, v133
	v_sub_u32_e32 v135, v134, v132
	v_cmp_gt_u32_e32 vcc, 16, v135
	v_sub_u32_e32 v136, v134, v131
	v_lshlrev_b32_e32 v136, 2, v136
	v_add_u32_e32 v136, 60, v136
	v_cndmask_b32_e32 v172, v210, v136, vcc
	v_add_u32_e32 v134, 5, v133
	v_sub_u32_e32 v135, v134, v132
	v_cmp_gt_u32_e32 vcc, 16, v135
	v_sub_u32_e32 v136, v134, v131
	v_lshlrev_b32_e32 v136, 2, v136
	v_add_u32_e32 v136, 60, v136
	v_cndmask_b32_e32 v173, v210, v136, vcc
	v_add_u32_e32 v134, 6, v133
	v_sub_u32_e32 v135, v134, v132
	v_cmp_gt_u32_e32 vcc, 16, v135
	v_sub_u32_e32 v136, v134, v131
	v_lshlrev_b32_e32 v136, 2, v136
	v_add_u32_e32 v136, 60, v136
	v_cndmask_b32_e32 v174, v210, v136, vcc
	v_add_u32_e32 v134, 7, v133
	v_sub_u32_e32 v135, v134, v132
	v_cmp_gt_u32_e32 vcc, 16, v135
	v_sub_u32_e32 v136, v134, v131
	v_lshlrev_b32_e32 v136, 2, v136
	v_add_u32_e32 v136, 60, v136
	v_cndmask_b32_e32 v175, v210, v136, vcc
	v_add_u32_e32 v134, 32, v133
	v_sub_u32_e32 v135, v134, v132
	v_cmp_gt_u32_e32 vcc, 16, v135
	v_sub_u32_e32 v136, v134, v131
	v_lshlrev_b32_e32 v136, 2, v136
	v_add_u32_e32 v136, 60, v136
	v_cndmask_b32_e32 v176, v210, v136, vcc
	v_add_u32_e32 v134, 33, v133
	v_sub_u32_e32 v135, v134, v132
; __device__ __forceinline__ void attn_phase(const Params& P, char* smem_raw) {
;     ...
;   int t = VBID;
;   __syncthreads();
;   if (t < 8192) {
;     const int h0 = t & 15;
;     for (int idx = tid; idx < 930; idx += VTHR) sm_rpb[idx] = (idx < 465) ? P.rpb[h0 * 465 + idx] * 1.4426950408889634f : -1e30f;
;     ATT_ISSUE(t, 0)
;     ATT_QLOAD(t)
;   }
;   for (; t < 8192; t += VGRID) {
;     const int h = t & 15, r = (t >> 4) & 127, b = t >> 11;
;     const int rs = min(max(r - 4, 0), 120);
;     bf16x8 qf[2];
;     qf[0] = qn[0]; qf[1] = qn[1];
;     f32x4 o[4];
; #pragma unroll
;     for (int td = 0; td < 4; ++td) o[td] = f32x4{0.f, 0.f, 0.f, 0.f};
;     float mrow[4], lrow[4];
; #pragma unroll
;     for (int reg = 0; reg < 4; ++reg) { mrow[reg] = -1e30f; lrow[reg] = 0.f; }
;     for (int ck = 0; ck < 6; ++ck) {
;       int lane_c = lane;
;       asm volatile("" : "+v"(lane_c));
;       __syncthreads();
; #pragma unroll
;       for (int i = 0; i < 4; ++i) {
;         const int idx = tid + 256 * i;
;         *reinterpret_cast<uint4*>(&sm_k[(idx >> 3) * LDSS + (idx & 7) * 8]) = kreg[i];
;         *reinterpret_cast<uint4*>(&sm_vt[(idx >> 4) * 136 + (idx & 15) * 8]) = vreg[i];
;       }
;       __syncthreads();
	v_cmp_gt_u32_e32 vcc, 16, v135
	v_sub_u32_e32 v136, v134, v131
	v_lshlrev_b32_e32 v136, 2, v136
	v_add_u32_e32 v136, 60, v136
	v_cndmask_b32_e32 v177, v210, v136, vcc
	v_add_u32_e32 v134, 34, v133
	v_sub_u32_e32 v135, v134, v132
	v_cmp_gt_u32_e32 vcc, 16, v135
	v_sub_u32_e32 v136, v134, v131
	v_lshlrev_b32_e32 v136, 2, v136
	v_add_u32_e32 v136, 60, v136
	v_cndmask_b32_e32 v178, v210, v136, vcc
	v_add_u32_e32 v134, 35, v133
	v_sub_u32_e32 v135, v134, v132
	v_cmp_gt_u32_e32 vcc, 16, v135
	v_sub_u32_e32 v136, v134, v131
	v_lshlrev_b32_e32 v136, 2, v136
	v_add_u32_e32 v136, 60, v136
	v_cndmask_b32_e32 v179, v210, v136, vcc
	v_add_u32_e32 v134, 36, v133
	v_sub_u32_e32 v135, v134, v132
	v_cmp_gt_u32_e32 vcc, 16, v135
	v_sub_u32_e32 v136, v134, v131
	v_lshlrev_b32_e32 v136, 2, v136
	v_add_u32_e32 v136, 60, v136
	v_cndmask_b32_e32 v180, v210, v136, vcc
	v_add_u32_e32 v134, 37, v133
	v_sub_u32_e32 v135, v134, v132
	v_cmp_gt_u32_e32 vcc, 16, v135
	v_sub_u32_e32 v136, v134, v131
	v_lshlrev_b32_e32 v136, 2, v136
	v_add_u32_e32 v136, 60, v136
	v_cndmask_b32_e32 v181, v210, v136, vcc
	v_add_u32_e32 v134, 38, v133
	v_sub_u32_e32 v135, v134, v132
	v_cmp_gt_u32_e32 vcc, 16, v135
	v_sub_u32_e32 v136, v134, v131
	v_lshlrev_b32_e32 v136, 2, v136
	v_add_u32_e32 v136, 60, v136
	v_cndmask_b32_e32 v182, v210, v136, vcc
	v_add_u32_e32 v134, 39, v133
	v_sub_u32_e32 v135, v134, v132
	v_cmp_gt_u32_e32 vcc, 16, v135
	v_sub_u32_e32 v136, v134, v131
	v_lshlrev_b32_e32 v136, 2, v136
	v_add_u32_e32 v136, 60, v136
	v_cndmask_b32_e32 v183, v210, v136, vcc
	v_mov_b32_e32 v143, 0xf149f2ca
	v_mov_b32_e32 v137, v112
	v_lshrrev_b32_e32 v138, 5, v137
	v_and_b32_e32 v139, 31, v137
	v_mul_u32_u24_e32 v140, 31, v138
	v_add_u32_e32 v140, v140, v139
	v_min_u32_e32 v140, 0x1d0, v140
	v_lshlrev_b32_e32 v140, 2, v140
	global_load_dword v141, v140, s[12:13]
	v_lshl_add_u32 v142, v137, 2, v117
	v_add_u32_e32 v142, 0x10000, v142
	v_cmp_eq_u32_e32 vcc, 31, v139
	s_waitcnt vmcnt(0)
	v_mul_f32_e32 v141, 0x3fb8aa3b, v141
	v_cndmask_b32_e32 v141, v141, v143, vcc
	ds_write_b32 v142, v141
	v_add_u32_e32 v137, 0x100, v112
	v_lshrrev_b32_e32 v138, 5, v137
	v_and_b32_e32 v139, 31, v137
	v_mul_u32_u24_e32 v140, 31, v138
	v_add_u32_e32 v140, v140, v139
	v_min_u32_e32 v140, 0x1d0, v140
	v_lshlrev_b32_e32 v140, 2, v140
	global_load_dword v141, v140, s[12:13]
	v_lshl_add_u32 v142, v137, 2, v117
	v_add_u32_e32 v142, 0x10000, v142
	v_cmp_eq_u32_e32 vcc, 31, v139
	s_waitcnt vmcnt(0)
	v_mul_f32_e32 v141, 0x3fb8aa3b, v141
	v_cndmask_b32_e32 v141, v141, v143, vcc
	ds_write_b32 v142, v141
	s_and_b32 s0, s3, 0xff
	s_lshr_b32 s1, s0, 2
	s_and_b32 s0, s0, 3
	s_lshl_b32 s0, s0, 5
	s_lshr_b32 vcc_lo, s3, 12
	s_add_u32 s0, s0, vcc_lo
	s_sub_i32 vcc_lo, s0, 4
	s_max_i32 vcc_lo, vcc_lo, 0
	s_min_i32 vcc_lo, vcc_lo, 0x78
	s_lshl_b32 vcc_hi, s1, 13
	s_lshl_b32 m0, vcc_lo, 6
	s_add_u32 m0, m0, vcc_hi
	s_mul_i32 m0, m0, 0x1800
	s_add_u32 s12, s4, m0
	s_addc_u32 s13, s5, 0
	s_lshl_b32 m0, s1, 24
	s_lshl_b32 s100, vcc_lo, 7
	s_add_u32 m0, m0, s100
	s_add_u32 s14, s6, m0
	s_addc_u32 s15, s7, 0
	s_lshl_b32 m0, s0, 6
	s_add_u32 m0, m0, vcc_hi
	s_mul_i32 m0, m0, 0x1800
	s_add_u32 s100, s4, m0
	s_addc_u32 s101, s5, 0
	global_load_dwordx4 v[64:67], v166, s[100:101]
	global_load_dwordx4 v[68:71], v166, s[100:101] offset:64
	s_and_b32 s0, s3, 0xff
	s_lshr_b32 s1, s0, 2
	s_and_b32 s0, s0, 3
	s_lshl_b32 s0, s0, 5
	s_lshr_b32 vcc_lo, s3, 12
	s_add_u32 s0, s0, vcc_lo
	s_sub_i32 vcc_lo, s0, 4
	s_max_i32 vcc_lo, vcc_lo, 0
	s_min_i32 vcc_lo, vcc_lo, 0x78
	s_lshl_b32 vcc_hi, s1, 13
	s_sub_i32 vcc_lo, vcc_lo, s0
	s_add_i32 vcc_lo, vcc_lo, 4
	s_lshl_b32 vcc_lo, vcc_lo, 7
	s_bfe_u32 m0, s3, 0x10008
	s_mul_i32 m0, m0, 0x12000
	s_add_i32 vcc_lo, vcc_lo, m0
	s_add_i32 vcc_lo, vcc_lo, 0x10010
	v_add_u32_e32 v184, vcc_lo, v168
	v_add_u32_e32 v185, vcc_lo, v169
	v_add_u32_e32 v186, vcc_lo, v170
	v_add_u32_e32 v187, vcc_lo, v171
	v_add_u32_e32 v188, vcc_lo, v172
	v_add_u32_e32 v189, vcc_lo, v173
	v_add_u32_e32 v190, vcc_lo, v174
	v_add_u32_e32 v191, vcc_lo, v175
	v_add_u32_e32 v192, vcc_lo, v176
	v_add_u32_e32 v193, vcc_lo, v177
	v_add_u32_e32 v194, vcc_lo, v178
	v_add_u32_e32 v195, vcc_lo, v179
	v_add_u32_e32 v196, vcc_lo, v180
	v_add_u32_e32 v197, vcc_lo, v181
	v_add_u32_e32 v198, vcc_lo, v182
	v_add_u32_e32 v199, vcc_lo, v183
	s_add_u32 s100, s12, 0x0
	s_addc_u32 s101, s13, 0
	s_add_u32 s0, s14, 0x0
	s_addc_u32 s1, s15, 0
	global_load_dwordx4 v[80:83], v154, s[100:101] offset:2048
	global_load_dwordx4 v[96:99], v158, s[0:1]
	global_load_dwordx4 v[84:87], v155, s[100:101] offset:2048
	global_load_dwordx4 v[100:103], v159, s[0:1]
	global_load_dwordx4 v[88:91], v156, s[100:101] offset:2048
	global_load_dwordx4 v[104:107], v160, s[0:1]
	global_load_dwordx4 v[92:95], v157, s[100:101] offset:2048
	global_load_dwordx4 v[108:111], v161, s[0:1]
	v_mov_b32_e32 v200, 0xf149f2ca
	v_mov_b32_e32 v201, 0
	v_mov_b32_e32 v32, 0
	v_mov_b32_e32 v33, 0
	v_mov_b32_e32 v34, 0
	v_mov_b32_e32 v35, 0
	v_mov_b32_e32 v36, 0
	v_mov_b32_e32 v37, 0
	v_mov_b32_e32 v38, 0
	v_mov_b32_e32 v39, 0
	v_mov_b32_e32 v40, 0
	v_mov_b32_e32 v41, 0
	v_mov_b32_e32 v42, 0
	v_mov_b32_e32 v43, 0
	v_mov_b32_e32 v44, 0
	v_mov_b32_e32 v45, 0
	v_mov_b32_e32 v46, 0
	v_mov_b32_e32 v47, 0
	s_waitcnt vmcnt(0)
	ds_write_b128 v150, v[80:83] offset:0
	ds_write_b128 v150, v[84:87] offset:4096
	ds_write_b128 v150, v[88:91] offset:8192
	ds_write_b128 v150, v[92:95] offset:12288
	ds_write_b128 v151, v[96:99] offset:0
	ds_write_b128 v151, v[100:103] offset:4096
	ds_write_b128 v151, v[104:107] offset:8192
	ds_write_b128 v151, v[108:111] offset:12288
	s_add_u32 s100, s12, 0xc0000
	s_addc_u32 s101, s13, 0
	s_add_u32 s0, s14, 0x100
	s_addc_u32 s1, s15, 0
	global_load_dwordx4 v[80:83], v154, s[100:101] offset:2048
	global_load_dwordx4 v[96:99], v158, s[0:1]
	global_load_dwordx4 v[84:87], v155, s[100:101] offset:2048
	global_load_dwordx4 v[100:103], v159, s[0:1]
	global_load_dwordx4 v[88:91], v156, s[100:101] offset:2048
	global_load_dwordx4 v[104:107], v160, s[0:1]
	global_load_dwordx4 v[92:95], v157, s[100:101] offset:2048
	global_load_dwordx4 v[108:111], v161, s[0:1]
	s_waitcnt lgkmcnt(0)
	s_barrier
; __device__ __forceinline__ void attn_phase(const Params& P, char* smem_raw) {
;     ...
;     for (int ck = 0; ck < 6; ++ck) {
;       int lane_c = lane;
;       asm volatile("" : "+v"(lane_c));
;       __syncthreads();
; #pragma unroll
;       for (int i = 0; i < 4; ++i) {
;         const int idx = tid + 256 * i;
;         *reinterpret_cast<uint4*>(&sm_k[(idx >> 3) * LDSS + (idx & 7) * 8]) = kreg[i];
;         *reinterpret_cast<uint4*>(&sm_vt[(idx >> 4) * 136 + (idx & 15) * 8]) = vreg[i];
;       }
;       __syncthreads();
;       f32x4 sacc[8];
; #pragma unroll
;       for (int t8 = 0; t8 < 8; ++t8) sacc[t8] = f32x4{0.f, 0.f, 0.f, 0.f};
; #pragma unroll
;       for (int s = 0; s < 2; ++s)
; #pragma unroll
;         for (int t8 = 0; t8 < 8; ++t8) {
;           const bf16x8 kf = *reinterpret_cast<const bf16x8*>(&sm_k[(t8 * 16 + (lane_c & 15)) * LDSS + s * 32 + (lane_c >> 4) * 8]);
;           sacc[t8] = __builtin_amdgcn_mfma_f32_16x16x32_bf16(qf[s], kf, sacc[t8], 0, 0, 0);
;         }
;       if (ck < 5) {
;         ATT_ISSUE(t, ck + 1)
;       } else if (t + VGRID < 8192) {
;         ATT_ISSUE(t + VGRID, 0)
;         ATT_QLOAD(t + VGRID)
;       }
;       if (ck < 4) {
;         const float* rb0 = sm_rpb + (rs + ck * 2 - r + 7) * 31;
; #pragma unroll
;         for (int t8 = 0; t8 < 8; ++t8)
; #pragma unroll
;           for (int reg = 0; reg < 4; ++reg)
;             sacc[t8][reg] += rb0[(t8 >> 2) * 31 + dco[reg][t8 & 3]];
;       }
	ds_read_b32 v0, v184 offset:384
	ds_read_b32 v1, v185 offset:384
	ds_read_b32 v2, v186 offset:384
	ds_read_b32 v3, v187 offset:384
	ds_read_b32 v4, v188 offset:384
	ds_read_b32 v5, v189 offset:384
	ds_read_b32 v6, v190 offset:384
	ds_read_b32 v7, v191 offset:384
	ds_read_b32 v8, v192 offset:384
	ds_read_b32 v9, v193 offset:384
	ds_read_b32 v10, v194 offset:384
	ds_read_b32 v11, v195 offset:384
	ds_read_b32 v12, v196 offset:384
	ds_read_b32 v13, v197 offset:384
	ds_read_b32 v14, v198 offset:384
	ds_read_b32 v15, v199 offset:384
	ds_read_b32 v16, v184 offset:512
	ds_read_b32 v17, v185 offset:512
	ds_read_b32 v18, v186 offset:512
	ds_read_b32 v19, v187 offset:512
	ds_read_b32 v20, v188 offset:512
	ds_read_b32 v21, v189 offset:512
	ds_read_b32 v22, v190 offset:512
	ds_read_b32 v23, v191 offset:512
	ds_read_b32 v24, v192 offset:512
	ds_read_b32 v25, v193 offset:512
	ds_read_b32 v26, v194 offset:512
	ds_read_b32 v27, v195 offset:512
	ds_read_b32 v28, v196 offset:512
	ds_read_b32 v29, v197 offset:512
	ds_read_b32 v30, v198 offset:512
	ds_read_b32 v31, v199 offset:512
	s_waitcnt lgkmcnt(0)
	s_waitcnt vmcnt(0)
.Lmy_att_tile:
	s_barrier
	s_waitcnt vmcnt(4)
	ds_write_b128 v150, v[80:83] offset:32768
	ds_write_b128 v150, v[84:87] offset:36864
	ds_write_b128 v150, v[88:91] offset:40960
	ds_write_b128 v150, v[92:95] offset:45056
	ds_write_b128 v151, v[96:99] offset:32768
	ds_write_b128 v151, v[100:103] offset:36864
	ds_write_b128 v151, v[104:107] offset:40960
	ds_write_b128 v151, v[108:111] offset:45056
	s_add_u32 s100, s12, 0x180000
	s_addc_u32 s101, s13, 0
	s_add_u32 s0, s14, 0x200
	s_addc_u32 s1, s15, 0
	global_load_dwordx4 v[80:83], v154, s[100:101] offset:2048
	global_load_dwordx4 v[96:99], v158, s[0:1]
	global_load_dwordx4 v[84:87], v155, s[100:101] offset:2048
	global_load_dwordx4 v[100:103], v159, s[0:1]
	global_load_dwordx4 v[88:91], v156, s[100:101] offset:2048
	global_load_dwordx4 v[104:107], v160, s[0:1]
	global_load_dwordx4 v[92:95], v157, s[100:101] offset:2048
	global_load_dwordx4 v[108:111], v161, s[0:1]
	s_and_b32 s0, s3, 0xff
	s_lshr_b32 s1, s0, 2
	s_and_b32 s0, s0, 3
	s_lshl_b32 s0, s0, 5
	s_lshr_b32 vcc_lo, s3, 12
	s_add_u32 s0, s0, vcc_lo
	s_sub_i32 vcc_lo, s0, 4
	s_max_i32 vcc_lo, vcc_lo, 0
	s_min_i32 vcc_lo, vcc_lo, 0x78
	s_lshl_b32 vcc_hi, s1, 13
	s_lshl_b32 m0, s1, 8
	s_add_u32 m0, m0, 0x8000
	s_mul_i32 m0, m0, 0x1800
	s_add_u32 s16, s4, m0
	s_addc_u32 s17, s5, 0
	s_lshl_b32 m0, s1, 19
	s_add_u32 s36, s8, m0
	s_addc_u32 s37, s9, 0
	s_lshl_b32 m0, s0, 6
	s_add_u32 m0, m0, vcc_hi
	s_lshl_b32 m0, m0, 11
	s_add_u32 s98, s10, m0
	s_addc_u32 s99, s11, 0
	ds_read_b128 v[112:115], v144 offset:0
	ds_read_b128 v[116:119], v145 offset:0
	ds_read_b128 v[120:123], v144 offset:512
	ds_read_b128 v[124:127], v145 offset:512
	ds_read_b128 v[128:131], v144 offset:4096
	ds_read_b128 v[132:135], v145 offset:4096
	ds_read_b128 v[136:139], v144 offset:4608
	ds_read_b128 v[140:143], v145 offset:4608
	s_waitcnt lgkmcnt(7)
	v_mfma_f32_16x16x32_bf16 v[0:3], v[112:115], v[64:67], v[0:3]
	ds_read_b128 v[112:115], v144 offset:8192
	s_waitcnt lgkmcnt(7)
	v_mfma_f32_16x16x32_bf16 v[0:3], v[116:119], v[68:71], v[0:3]
	ds_read_b128 v[116:119], v145 offset:8192
	s_waitcnt lgkmcnt(7)
	v_mfma_f32_16x16x32_bf16 v[4:7], v[120:123], v[64:67], v[4:7]
	ds_read_b128 v[120:123], v144 offset:8704
	s_waitcnt lgkmcnt(7)
	v_mfma_f32_16x16x32_bf16 v[4:7], v[124:127], v[68:71], v[4:7]
	ds_read_b128 v[124:127], v145 offset:8704
	s_waitcnt lgkmcnt(7)
	v_mfma_f32_16x16x32_bf16 v[8:11], v[128:131], v[64:67], v[8:11]
	ds_read_b128 v[128:131], v144 offset:12288
	s_waitcnt lgkmcnt(7)
	v_mfma_f32_16x16x32_bf16 v[8:11], v[132:135], v[68:71], v[8:11]
	ds_read_b128 v[132:135], v145 offset:12288
	s_waitcnt lgkmcnt(7)
	v_mfma_f32_16x16x32_bf16 v[12:15], v[136:139], v[64:67], v[12:15]
	ds_read_b128 v[136:139], v144 offset:12800
	s_waitcnt lgkmcnt(7)
	v_mfma_f32_16x16x32_bf16 v[12:15], v[140:143], v[68:71], v[12:15]
	ds_read_b128 v[140:143], v145 offset:12800
	s_waitcnt lgkmcnt(7)
	v_mfma_f32_16x16x32_bf16 v[16:19], v[112:115], v[64:67], v[16:19]
	s_waitcnt lgkmcnt(6)
	v_mfma_f32_16x16x32_bf16 v[16:19], v[116:119], v[68:71], v[16:19]
	s_waitcnt lgkmcnt(5)
	v_mfma_f32_16x16x32_bf16 v[20:23], v[120:123], v[64:67], v[20:23]
	s_waitcnt lgkmcnt(4)
	v_mfma_f32_16x16x32_bf16 v[20:23], v[124:127], v[68:71], v[20:23]
	s_waitcnt lgkmcnt(3)
	v_mfma_f32_16x16x32_bf16 v[24:27], v[128:131], v[64:67], v[24:27]
	s_waitcnt lgkmcnt(2)
	v_mfma_f32_16x16x32_bf16 v[24:27], v[132:135], v[68:71], v[24:27]
	s_waitcnt lgkmcnt(1)
	v_mfma_f32_16x16x32_bf16 v[28:31], v[136:139], v[64:67], v[28:31]
	s_waitcnt lgkmcnt(0)
; __device__ __forceinline__ void attn_phase(const Params& P, char* smem_raw) {
;     ...
; #pragma unroll
;       for (int reg = 0; reg < 4; ++reg) {
;         float mx = sacc[0][reg];
; #pragma unroll
;         for (int t8 = 1; t8 < 8; ++t8) mx = fmaxf(mx, sacc[t8][reg]);
;         mx = row16_max(mx);
;         const float mnew = fmaxf(mrow[reg], mx);
;         const float alpha = __builtin_amdgcn_exp2f(mrow[reg] - mnew);
;         mrow[reg] = mnew;
;         float rsum = 0.f;
; #pragma unroll
;         for (int t8 = 0; t8 < 8; ++t8) {
;           const float p = __builtin_amdgcn_exp2f(sacc[t8][reg] - mnew);
;           rsum += p;
;           sm_p[(wid * 16 + (lane_c >> 4) * 4 + reg) * 136 + t8 * 16 + (lane_c & 15)] = f2bf(p);
;         }
;         rsum = row16_sum(rsum);
;         lrow[reg] = lrow[reg] * alpha + rsum;
; #pragma unroll
;         for (int td = 0; td < 4; ++td) o[td][reg] *= alpha;
;       }
;       asm volatile("s_waitcnt lgkmcnt(0)" ::: "memory");
; #pragma unroll
;       for (int s4 = 0; s4 < 4; ++s4) {
;         const bf16x8 pf = *reinterpret_cast<const bf16x8*>(&sm_p[(wid * 16 + (lane_c & 15)) * 136 + s4 * 32 + (lane_c >> 4) * 8]);
; #pragma unroll
;         for (int td = 0; td < 4; ++td) {
;           const bf16x8 vf = *reinterpret_cast<const bf16x8*>(&sm_vt[(td * 16 + (lane_c & 15)) * 136 + s4 * 32 + (lane_c >> 4) * 8]);
;           o[td] = __builtin_amdgcn_mfma_f32_16x16x32_bf16(pf, vf, o[td], 0, 0, 0);
;         }
;       }
	v_mfma_f32_16x16x32_bf16 v[28:31], v[140:143], v[68:71], v[28:31]
	s_nop 7
	v_max3_f32 v203, v0, v1, v2
	v_max3_f32 v203, v203, v3, v4
	v_max3_f32 v203, v203, v5, v6
	v_max3_f32 v203, v203, v7, v8
	v_max3_f32 v203, v203, v9, v10
	v_max3_f32 v203, v203, v11, v12
	v_max3_f32 v203, v203, v13, v14
	v_max3_f32 v203, v203, v15, v16
	v_max3_f32 v203, v203, v17, v18
	v_max3_f32 v203, v203, v19, v20
	v_max3_f32 v203, v203, v21, v22
	v_max3_f32 v203, v203, v23, v24
	v_max3_f32 v203, v203, v25, v26
	v_max3_f32 v203, v203, v27, v28
	v_max3_f32 v203, v203, v29, v30
	v_max_f32_e32 v203, v203, v31
	v_mov_b32_e32 v205, v203
	s_nop 1
	v_permlane16_swap_b32_e32 v203, v205
	v_max_f32_e32 v203, v203, v205
	v_mov_b32_e32 v205, v203
	s_nop 1
	v_permlane32_swap_b32_e32 v203, v205
	v_max_f32_e32 v203, v203, v205
	v_max_f32_e32 v208, v200, v203
	v_sub_f32_e32 v202, v200, v208
	v_exp_f32_e32 v202, v202
	v_mov_b32_e32 v200, v208
	v_sub_f32_e32 v0, v0, v208
	v_sub_f32_e32 v1, v1, v208
	v_sub_f32_e32 v2, v2, v208
	v_sub_f32_e32 v3, v3, v208
	v_sub_f32_e32 v4, v4, v208
	v_sub_f32_e32 v5, v5, v208
	v_sub_f32_e32 v6, v6, v208
	v_sub_f32_e32 v7, v7, v208
	v_sub_f32_e32 v8, v8, v208
	v_sub_f32_e32 v9, v9, v208
	v_sub_f32_e32 v10, v10, v208
	v_sub_f32_e32 v11, v11, v208
	v_sub_f32_e32 v12, v12, v208
	v_sub_f32_e32 v13, v13, v208
	v_sub_f32_e32 v14, v14, v208
	v_sub_f32_e32 v15, v15, v208
	v_sub_f32_e32 v16, v16, v208
	v_sub_f32_e32 v17, v17, v208
	v_sub_f32_e32 v18, v18, v208
	v_sub_f32_e32 v19, v19, v208
	v_sub_f32_e32 v20, v20, v208
	v_sub_f32_e32 v21, v21, v208
	v_sub_f32_e32 v22, v22, v208
	v_sub_f32_e32 v23, v23, v208
	v_sub_f32_e32 v24, v24, v208
	v_sub_f32_e32 v25, v25, v208
	v_sub_f32_e32 v26, v26, v208
	v_sub_f32_e32 v27, v27, v208
	v_sub_f32_e32 v28, v28, v208
	v_sub_f32_e32 v29, v29, v208
	v_sub_f32_e32 v30, v30, v208
	v_sub_f32_e32 v31, v31, v208
	v_exp_f32_e32 v0, v0
	v_exp_f32_e32 v1, v1
	v_exp_f32_e32 v2, v2
	v_exp_f32_e32 v3, v3
	v_exp_f32_e32 v4, v4
	v_exp_f32_e32 v5, v5
	v_exp_f32_e32 v6, v6
	v_exp_f32_e32 v7, v7
	v_exp_f32_e32 v8, v8
	v_exp_f32_e32 v9, v9
	v_exp_f32_e32 v10, v10
	v_exp_f32_e32 v11, v11
	v_exp_f32_e32 v12, v12
	v_exp_f32_e32 v13, v13
	v_exp_f32_e32 v14, v14
	v_exp_f32_e32 v15, v15
	v_exp_f32_e32 v16, v16
	v_exp_f32_e32 v17, v17
	v_exp_f32_e32 v18, v18
	v_exp_f32_e32 v19, v19
	v_exp_f32_e32 v20, v20
	v_exp_f32_e32 v21, v21
	v_exp_f32_e32 v22, v22
	v_exp_f32_e32 v23, v23
	v_exp_f32_e32 v24, v24
	v_exp_f32_e32 v25, v25
	v_exp_f32_e32 v26, v26
	v_exp_f32_e32 v27, v27
	v_exp_f32_e32 v28, v28
	v_exp_f32_e32 v29, v29
	v_exp_f32_e32 v30, v30
	v_exp_f32_e32 v31, v31
	v_mul_f32_e32 v201, v201, v202
	v_mul_f32_e32 v32, v32, v202
	v_mul_f32_e32 v33, v33, v202
	v_mul_f32_e32 v34, v34, v202
	v_mul_f32_e32 v35, v35, v202
	v_mul_f32_e32 v36, v36, v202
	v_mul_f32_e32 v37, v37, v202
	v_mul_f32_e32 v38, v38, v202
	v_mul_f32_e32 v39, v39, v202
	v_mul_f32_e32 v40, v40, v202
	v_mul_f32_e32 v41, v41, v202
	v_mul_f32_e32 v42, v42, v202
	v_mul_f32_e32 v43, v43, v202
	v_mul_f32_e32 v44, v44, v202
	v_mul_f32_e32 v45, v45, v202
	v_mul_f32_e32 v46, v46, v202
	v_mul_f32_e32 v47, v47, v202
	v_add_f32_e32 v203, v0, v1
	v_add_f32_e32 v205, v2, v3
	v_add_f32_e32 v203, v203, v4
	v_add_f32_e32 v205, v205, v5
	v_add_f32_e32 v203, v203, v6
	v_add_f32_e32 v205, v205, v7
	v_add_f32_e32 v203, v203, v8
	v_add_f32_e32 v205, v205, v9
	v_add_f32_e32 v203, v203, v10
	v_add_f32_e32 v205, v205, v11
	v_add_f32_e32 v203, v203, v12
	v_add_f32_e32 v205, v205, v13
	v_add_f32_e32 v203, v203, v14
	v_add_f32_e32 v205, v205, v15
	v_add_f32_e32 v203, v203, v16
	v_add_f32_e32 v205, v205, v17
	v_add_f32_e32 v203, v203, v18
	v_add_f32_e32 v205, v205, v19
	v_add_f32_e32 v203, v203, v20
	v_add_f32_e32 v205, v205, v21
	v_add_f32_e32 v203, v203, v22
	v_add_f32_e32 v205, v205, v23
	v_add_f32_e32 v203, v203, v24
	v_add_f32_e32 v205, v205, v25
	v_add_f32_e32 v203, v203, v26
	v_add_f32_e32 v205, v205, v27
	v_add_f32_e32 v203, v203, v28
	v_add_f32_e32 v205, v205, v29
	v_add_f32_e32 v203, v203, v30
	v_add_f32_e32 v205, v205, v31
	v_add_f32_e32 v203, v203, v205
	v_add_f32_e32 v201, v201, v203
	v_cvt_pk_bf16_f32 v48, v0, v1
	v_cvt_pk_bf16_f32 v49, v2, v3
	v_cvt_pk_bf16_f32 v50, v4, v5
	v_cvt_pk_bf16_f32 v51, v6, v7
	v_cvt_pk_bf16_f32 v52, v8, v9
	v_cvt_pk_bf16_f32 v53, v10, v11
	v_cvt_pk_bf16_f32 v54, v12, v13
	v_cvt_pk_bf16_f32 v55, v14, v15
	v_cvt_pk_bf16_f32 v56, v16, v17
	v_cvt_pk_bf16_f32 v57, v18, v19
	v_cvt_pk_bf16_f32 v58, v20, v21
	v_cvt_pk_bf16_f32 v59, v22, v23
	v_cvt_pk_bf16_f32 v60, v24, v25
	v_cvt_pk_bf16_f32 v61, v26, v27
	v_cvt_pk_bf16_f32 v62, v28, v29
	v_cvt_pk_bf16_f32 v63, v30, v31
	ds_read_b128 v[112:115], v146 offset:0
	ds_read_b128 v[116:119], v146 offset:4096
	ds_read_b128 v[120:123], v146 offset:8192
	ds_read_b128 v[124:127], v146 offset:12288
	ds_read_b128 v[128:131], v147 offset:0
	ds_read_b128 v[132:135], v147 offset:4096
	ds_read_b128 v[136:139], v147 offset:8192
	ds_read_b128 v[140:143], v147 offset:12288
	s_waitcnt lgkmcnt(7)
	v_mfma_f32_16x16x32_bf16 v[32:35], v[112:115], v[48:51], v[32:35]
	ds_read_b128 v[112:115], v148 offset:0
	s_waitcnt lgkmcnt(7)
	v_mfma_f32_16x16x32_bf16 v[36:39], v[116:119], v[48:51], v[36:39]
	ds_read_b128 v[116:119], v148 offset:4096
	s_waitcnt lgkmcnt(7)
	v_mfma_f32_16x16x32_bf16 v[40:43], v[120:123], v[48:51], v[40:43]
	ds_read_b128 v[120:123], v148 offset:8192
	s_waitcnt lgkmcnt(7)
	v_mfma_f32_16x16x32_bf16 v[44:47], v[124:127], v[48:51], v[44:47]
	ds_read_b128 v[124:127], v148 offset:12288
	s_waitcnt lgkmcnt(7)
	v_mfma_f32_16x16x32_bf16 v[32:35], v[128:131], v[52:55], v[32:35]
	ds_read_b128 v[128:131], v149 offset:0
	s_waitcnt lgkmcnt(7)
; __device__ __forceinline__ void attn_phase(const Params& P, char* smem_raw) {
;     ...
;     for (int ck = 0; ck < 6; ++ck) {
;       int lane_c = lane;
;       asm volatile("" : "+v"(lane_c));
;       __syncthreads();
; #pragma unroll
;       for (int i = 0; i < 4; ++i) {
;         const int idx = tid + 256 * i;
;         *reinterpret_cast<uint4*>(&sm_k[(idx >> 3) * LDSS + (idx & 7) * 8]) = kreg[i];
;         *reinterpret_cast<uint4*>(&sm_vt[(idx >> 4) * 136 + (idx & 15) * 8]) = vreg[i];
;       }
;       __syncthreads();
;       f32x4 sacc[8];
; #pragma unroll
;       for (int t8 = 0; t8 < 8; ++t8) sacc[t8] = f32x4{0.f, 0.f, 0.f, 0.f};
; #pragma unroll
;       for (int s = 0; s < 2; ++s)
; #pragma unroll
;         for (int t8 = 0; t8 < 8; ++t8) {
;           const bf16x8 kf = *reinterpret_cast<const bf16x8*>(&sm_k[(t8 * 16 + (lane_c & 15)) * LDSS + s * 32 + (lane_c >> 4) * 8]);
;           sacc[t8] = __builtin_amdgcn_mfma_f32_16x16x32_bf16(qf[s], kf, sacc[t8], 0, 0, 0);
;         }
;       if (ck < 5) {
;         ATT_ISSUE(t, ck + 1)
;       } else if (t + VGRID < 8192) {
;         ATT_ISSUE(t + VGRID, 0)
;         ATT_QLOAD(t + VGRID)
;       }
;       if (ck < 4) {
;         const float* rb0 = sm_rpb + (rs + ck * 2 - r + 7) * 31;
; #pragma unroll
;         for (int t8 = 0; t8 < 8; ++t8)
; #pragma unroll
;           for (int reg = 0; reg < 4; ++reg)
;             sacc[t8][reg] += rb0[(t8 >> 2) * 31 + dco[reg][t8 & 3]];
;       }
; #pragma unroll
;       for (int reg = 0; reg < 4; ++reg) {
;         float mx = sacc[0][reg];
; #pragma unroll
;         for (int t8 = 1; t8 < 8; ++t8) mx = fmaxf(mx, sacc[t8][reg]);
;         mx = row16_max(mx);
;         const float mnew = fmaxf(mrow[reg], mx);
;         const float alpha = __builtin_amdgcn_exp2f(mrow[reg] - mnew);
;         mrow[reg] = mnew;
;         float rsum = 0.f;
; #pragma unroll
;         for (int t8 = 0; t8 < 8; ++t8) {
;           const float p = __builtin_amdgcn_exp2f(sacc[t8][reg] - mnew);
;           rsum += p;
;           sm_p[(wid * 16 + (lane_c >> 4) * 4 + reg) * 136 + t8 * 16 + (lane_c & 15)] = f2bf(p);
;         }
;         rsum = row16_sum(rsum);
;         lrow[reg] = lrow[reg] * alpha + rsum;
; #pragma unroll
;         for (int td = 0; td < 4; ++td) o[td][reg] *= alpha;
;       }
;       asm volatile("s_waitcnt lgkmcnt(0)" ::: "memory");
; #pragma unroll
;       for (int s4 = 0; s4 < 4; ++s4) {
	v_mfma_f32_16x16x32_bf16 v[36:39], v[132:135], v[52:55], v[36:39]
	ds_read_b128 v[132:135], v149 offset:4096
	s_waitcnt lgkmcnt(7)
	v_mfma_f32_16x16x32_bf16 v[40:43], v[136:139], v[52:55], v[40:43]
	ds_read_b128 v[136:139], v149 offset:8192
	s_waitcnt lgkmcnt(7)
	v_mfma_f32_16x16x32_bf16 v[44:47], v[140:143], v[52:55], v[44:47]
	ds_read_b128 v[140:143], v149 offset:12288
	s_waitcnt lgkmcnt(7)
	v_mfma_f32_16x16x32_bf16 v[32:35], v[112:115], v[56:59], v[32:35]
	s_waitcnt lgkmcnt(6)
	v_mfma_f32_16x16x32_bf16 v[36:39], v[116:119], v[56:59], v[36:39]
	s_waitcnt lgkmcnt(5)
	v_mfma_f32_16x16x32_bf16 v[40:43], v[120:123], v[56:59], v[40:43]
	s_waitcnt lgkmcnt(4)
	v_mfma_f32_16x16x32_bf16 v[44:47], v[124:127], v[56:59], v[44:47]
	s_waitcnt lgkmcnt(3)
	v_mfma_f32_16x16x32_bf16 v[32:35], v[128:131], v[60:63], v[32:35]
	s_waitcnt lgkmcnt(2)
	v_mfma_f32_16x16x32_bf16 v[36:39], v[132:135], v[60:63], v[36:39]
	s_waitcnt lgkmcnt(1)
	v_mfma_f32_16x16x32_bf16 v[40:43], v[136:139], v[60:63], v[40:43]
	s_waitcnt lgkmcnt(0)
	v_mfma_f32_16x16x32_bf16 v[44:47], v[140:143], v[60:63], v[44:47]
	ds_read_b32 v0, v184 offset:640
	ds_read_b32 v1, v185 offset:640
	ds_read_b32 v2, v186 offset:640
	ds_read_b32 v3, v187 offset:640
	ds_read_b32 v4, v188 offset:640
	ds_read_b32 v5, v189 offset:640
	ds_read_b32 v6, v190 offset:640
	ds_read_b32 v7, v191 offset:640
	ds_read_b32 v8, v192 offset:640
	ds_read_b32 v9, v193 offset:640
	ds_read_b32 v10, v194 offset:640
	ds_read_b32 v11, v195 offset:640
	ds_read_b32 v12, v196 offset:640
	ds_read_b32 v13, v197 offset:640
	ds_read_b32 v14, v198 offset:640
	ds_read_b32 v15, v199 offset:640
	ds_read_b32 v16, v184 offset:768
	ds_read_b32 v17, v185 offset:768
	ds_read_b32 v18, v186 offset:768
	ds_read_b32 v19, v187 offset:768
	ds_read_b32 v20, v188 offset:768
	ds_read_b32 v21, v189 offset:768
	ds_read_b32 v22, v190 offset:768
	ds_read_b32 v23, v191 offset:768
	ds_read_b32 v24, v192 offset:768
	ds_read_b32 v25, v193 offset:768
	ds_read_b32 v26, v194 offset:768
	ds_read_b32 v27, v195 offset:768
	ds_read_b32 v28, v196 offset:768
	ds_read_b32 v29, v197 offset:768
	ds_read_b32 v30, v198 offset:768
	ds_read_b32 v31, v199 offset:768
	s_waitcnt lgkmcnt(0)
	s_barrier
	s_waitcnt vmcnt(0)
	ds_write_b128 v150, v[80:83] offset:0
	ds_write_b128 v150, v[84:87] offset:4096
	ds_write_b128 v150, v[88:91] offset:8192
	ds_write_b128 v150, v[92:95] offset:12288
	ds_write_b128 v151, v[96:99] offset:0
	ds_write_b128 v151, v[100:103] offset:4096
	ds_write_b128 v151, v[104:107] offset:8192
	ds_write_b128 v151, v[108:111] offset:12288
	s_add_u32 s100, s12, 0x240000
	s_addc_u32 s101, s13, 0
	s_add_u32 s0, s14, 0x300
	s_addc_u32 s1, s15, 0
	global_load_dwordx4 v[80:83], v154, s[100:101] offset:2048
	global_load_dwordx4 v[96:99], v158, s[0:1]
	global_load_dwordx4 v[84:87], v155, s[100:101] offset:2048
	global_load_dwordx4 v[100:103], v159, s[0:1]
	global_load_dwordx4 v[88:91], v156, s[100:101] offset:2048
	global_load_dwordx4 v[104:107], v160, s[0:1]
	global_load_dwordx4 v[92:95], v157, s[100:101] offset:2048
	global_load_dwordx4 v[108:111], v161, s[0:1]
	ds_read_b128 v[112:115], v144 offset:32768
	ds_read_b128 v[116:119], v145 offset:32768
	ds_read_b128 v[120:123], v144 offset:33280
	ds_read_b128 v[124:127], v145 offset:33280
	ds_read_b128 v[128:131], v144 offset:36864
	ds_read_b128 v[132:135], v145 offset:36864
	ds_read_b128 v[136:139], v144 offset:37376
	ds_read_b128 v[140:143], v145 offset:37376
	s_waitcnt lgkmcnt(7)
	v_mfma_f32_16x16x32_bf16 v[0:3], v[112:115], v[64:67], v[0:3]
	ds_read_b128 v[112:115], v144 offset:40960
	s_waitcnt lgkmcnt(7)
	v_mfma_f32_16x16x32_bf16 v[0:3], v[116:119], v[68:71], v[0:3]
	ds_read_b128 v[116:119], v145 offset:40960
	s_waitcnt lgkmcnt(7)
	v_mfma_f32_16x16x32_bf16 v[4:7], v[120:123], v[64:67], v[4:7]
	ds_read_b128 v[120:123], v144 offset:41472
	s_waitcnt lgkmcnt(7)
	v_mfma_f32_16x16x32_bf16 v[4:7], v[124:127], v[68:71], v[4:7]
	ds_read_b128 v[124:127], v145 offset:41472
	s_waitcnt lgkmcnt(7)
	v_mfma_f32_16x16x32_bf16 v[8:11], v[128:131], v[64:67], v[8:11]
	ds_read_b128 v[128:131], v144 offset:45056
	s_waitcnt lgkmcnt(7)
	v_mfma_f32_16x16x32_bf16 v[8:11], v[132:135], v[68:71], v[8:11]
	ds_read_b128 v[132:135], v145 offset:45056
	s_waitcnt lgkmcnt(7)
	v_mfma_f32_16x16x32_bf16 v[12:15], v[136:139], v[64:67], v[12:15]
	ds_read_b128 v[136:139], v144 offset:45568
	s_waitcnt lgkmcnt(7)
	v_mfma_f32_16x16x32_bf16 v[12:15], v[140:143], v[68:71], v[12:15]
	ds_read_b128 v[140:143], v145 offset:45568
	s_waitcnt lgkmcnt(7)
	v_mfma_f32_16x16x32_bf16 v[16:19], v[112:115], v[64:67], v[16:19]
	s_waitcnt lgkmcnt(6)
	v_mfma_f32_16x16x32_bf16 v[16:19], v[116:119], v[68:71], v[16:19]
	s_waitcnt lgkmcnt(5)
	v_mfma_f32_16x16x32_bf16 v[20:23], v[120:123], v[64:67], v[20:23]
	s_waitcnt lgkmcnt(4)
	v_mfma_f32_16x16x32_bf16 v[20:23], v[124:127], v[68:71], v[20:23]
	s_waitcnt lgkmcnt(3)
	v_mfma_f32_16x16x32_bf16 v[24:27], v[128:131], v[64:67], v[24:27]
	s_waitcnt lgkmcnt(2)
	v_mfma_f32_16x16x32_bf16 v[24:27], v[132:135], v[68:71], v[24:27]
	s_waitcnt lgkmcnt(1)
	v_mfma_f32_16x16x32_bf16 v[28:31], v[136:139], v[64:67], v[28:31]
	s_waitcnt lgkmcnt(0)
; __device__ __forceinline__ void attn_phase(const Params& P, char* smem_raw) {
;     ...
; #pragma unroll
;       for (int reg = 0; reg < 4; ++reg) {
;         float mx = sacc[0][reg];
; #pragma unroll
;         for (int t8 = 1; t8 < 8; ++t8) mx = fmaxf(mx, sacc[t8][reg]);
;         mx = row16_max(mx);
;         const float mnew = fmaxf(mrow[reg], mx);
;         const float alpha = __builtin_amdgcn_exp2f(mrow[reg] - mnew);
;         mrow[reg] = mnew;
;         float rsum = 0.f;
; #pragma unroll
;         for (int t8 = 0; t8 < 8; ++t8) {
;           const float p = __builtin_amdgcn_exp2f(sacc[t8][reg] - mnew);
;           rsum += p;
;           sm_p[(wid * 16 + (lane_c >> 4) * 4 + reg) * 136 + t8 * 16 + (lane_c & 15)] = f2bf(p);
;         }
;         rsum = row16_sum(rsum);
;         lrow[reg] = lrow[reg] * alpha + rsum;
; #pragma unroll
;         for (int td = 0; td < 4; ++td) o[td][reg] *= alpha;
;       }
;       asm volatile("s_waitcnt lgkmcnt(0)" ::: "memory");
; #pragma unroll
;       for (int s4 = 0; s4 < 4; ++s4) {
;         const bf16x8 pf = *reinterpret_cast<const bf16x8*>(&sm_p[(wid * 16 + (lane_c & 15)) * 136 + s4 * 32 + (lane_c >> 4) * 8]);
; #pragma unroll
;         for (int td = 0; td < 4; ++td) {
;           const bf16x8 vf = *reinterpret_cast<const bf16x8*>(&sm_vt[(td * 16 + (lane_c & 15)) * 136 + s4 * 32 + (lane_c >> 4) * 8]);
;           o[td] = __builtin_amdgcn_mfma_f32_16x16x32_bf16(pf, vf, o[td], 0, 0, 0);
;         }
;       }
	v_mfma_f32_16x16x32_bf16 v[28:31], v[140:143], v[68:71], v[28:31]
	s_nop 7
	v_max3_f32 v203, v0, v1, v2
	v_max3_f32 v203, v203, v3, v4
	v_max3_f32 v203, v203, v5, v6
	v_max3_f32 v203, v203, v7, v8
	v_max3_f32 v203, v203, v9, v10
	v_max3_f32 v203, v203, v11, v12
	v_max3_f32 v203, v203, v13, v14
	v_max3_f32 v203, v203, v15, v16
	v_max3_f32 v203, v203, v17, v18
	v_max3_f32 v203, v203, v19, v20
	v_max3_f32 v203, v203, v21, v22
	v_max3_f32 v203, v203, v23, v24
	v_max3_f32 v203, v203, v25, v26
	v_max3_f32 v203, v203, v27, v28
	v_max3_f32 v203, v203, v29, v30
	v_max_f32_e32 v203, v203, v31
	v_mov_b32_e32 v205, v203
	s_nop 1
	v_permlane16_swap_b32_e32 v203, v205
	v_max_f32_e32 v203, v203, v205
	v_mov_b32_e32 v205, v203
	s_nop 1
	v_permlane32_swap_b32_e32 v203, v205
	v_max_f32_e32 v203, v203, v205
	v_max_f32_e32 v208, v200, v203
	v_sub_f32_e32 v202, v200, v208
	v_exp_f32_e32 v202, v202
	v_mov_b32_e32 v200, v208
	v_sub_f32_e32 v0, v0, v208
	v_sub_f32_e32 v1, v1, v208
	v_sub_f32_e32 v2, v2, v208
	v_sub_f32_e32 v3, v3, v208
	v_sub_f32_e32 v4, v4, v208
	v_sub_f32_e32 v5, v5, v208
	v_sub_f32_e32 v6, v6, v208
	v_sub_f32_e32 v7, v7, v208
	v_sub_f32_e32 v8, v8, v208
	v_sub_f32_e32 v9, v9, v208
	v_sub_f32_e32 v10, v10, v208
	v_sub_f32_e32 v11, v11, v208
	v_sub_f32_e32 v12, v12, v208
	v_sub_f32_e32 v13, v13, v208
	v_sub_f32_e32 v14, v14, v208
	v_sub_f32_e32 v15, v15, v208
	v_sub_f32_e32 v16, v16, v208
	v_sub_f32_e32 v17, v17, v208
	v_sub_f32_e32 v18, v18, v208
	v_sub_f32_e32 v19, v19, v208
	v_sub_f32_e32 v20, v20, v208
	v_sub_f32_e32 v21, v21, v208
	v_sub_f32_e32 v22, v22, v208
	v_sub_f32_e32 v23, v23, v208
	v_sub_f32_e32 v24, v24, v208
	v_sub_f32_e32 v25, v25, v208
	v_sub_f32_e32 v26, v26, v208
	v_sub_f32_e32 v27, v27, v208
	v_sub_f32_e32 v28, v28, v208
	v_sub_f32_e32 v29, v29, v208
	v_sub_f32_e32 v30, v30, v208
	v_sub_f32_e32 v31, v31, v208
	v_exp_f32_e32 v0, v0
	v_exp_f32_e32 v1, v1
	v_exp_f32_e32 v2, v2
	v_exp_f32_e32 v3, v3
	v_exp_f32_e32 v4, v4
	v_exp_f32_e32 v5, v5
	v_exp_f32_e32 v6, v6
	v_exp_f32_e32 v7, v7
	v_exp_f32_e32 v8, v8
	v_exp_f32_e32 v9, v9
	v_exp_f32_e32 v10, v10
	v_exp_f32_e32 v11, v11
	v_exp_f32_e32 v12, v12
	v_exp_f32_e32 v13, v13
	v_exp_f32_e32 v14, v14
	v_exp_f32_e32 v15, v15
	v_exp_f32_e32 v16, v16
	v_exp_f32_e32 v17, v17
	v_exp_f32_e32 v18, v18
	v_exp_f32_e32 v19, v19
	v_exp_f32_e32 v20, v20
	v_exp_f32_e32 v21, v21
	v_exp_f32_e32 v22, v22
	v_exp_f32_e32 v23, v23
	v_exp_f32_e32 v24, v24
	v_exp_f32_e32 v25, v25
	v_exp_f32_e32 v26, v26
	v_exp_f32_e32 v27, v27
	v_exp_f32_e32 v28, v28
	v_exp_f32_e32 v29, v29
	v_exp_f32_e32 v30, v30
	v_exp_f32_e32 v31, v31
	v_mul_f32_e32 v201, v201, v202
	v_mul_f32_e32 v32, v32, v202
	v_mul_f32_e32 v33, v33, v202
	v_mul_f32_e32 v34, v34, v202
	v_mul_f32_e32 v35, v35, v202
	v_mul_f32_e32 v36, v36, v202
	v_mul_f32_e32 v37, v37, v202
	v_mul_f32_e32 v38, v38, v202
	v_mul_f32_e32 v39, v39, v202
	v_mul_f32_e32 v40, v40, v202
	v_mul_f32_e32 v41, v41, v202
	v_mul_f32_e32 v42, v42, v202
	v_mul_f32_e32 v43, v43, v202
	v_mul_f32_e32 v44, v44, v202
	v_mul_f32_e32 v45, v45, v202
	v_mul_f32_e32 v46, v46, v202
	v_mul_f32_e32 v47, v47, v202
	v_add_f32_e32 v203, v0, v1
	v_add_f32_e32 v205, v2, v3
	v_add_f32_e32 v203, v203, v4
	v_add_f32_e32 v205, v205, v5
	v_add_f32_e32 v203, v203, v6
	v_add_f32_e32 v205, v205, v7
	v_add_f32_e32 v203, v203, v8
	v_add_f32_e32 v205, v205, v9
	v_add_f32_e32 v203, v203, v10
	v_add_f32_e32 v205, v205, v11
	v_add_f32_e32 v203, v203, v12
	v_add_f32_e32 v205, v205, v13
	v_add_f32_e32 v203, v203, v14
	v_add_f32_e32 v205, v205, v15
	v_add_f32_e32 v203, v203, v16
	v_add_f32_e32 v205, v205, v17
	v_add_f32_e32 v203, v203, v18
	v_add_f32_e32 v205, v205, v19
	v_add_f32_e32 v203, v203, v20
	v_add_f32_e32 v205, v205, v21
	v_add_f32_e32 v203, v203, v22
	v_add_f32_e32 v205, v205, v23
	v_add_f32_e32 v203, v203, v24
	v_add_f32_e32 v205, v205, v25
	v_add_f32_e32 v203, v203, v26
	v_add_f32_e32 v205, v205, v27
	v_add_f32_e32 v203, v203, v28
	v_add_f32_e32 v205, v205, v29
	v_add_f32_e32 v203, v203, v30
	v_add_f32_e32 v205, v205, v31
	v_add_f32_e32 v203, v203, v205
	v_add_f32_e32 v201, v201, v203
	v_cvt_pk_bf16_f32 v48, v0, v1
	v_cvt_pk_bf16_f32 v49, v2, v3
	v_cvt_pk_bf16_f32 v50, v4, v5
	v_cvt_pk_bf16_f32 v51, v6, v7
	v_cvt_pk_bf16_f32 v52, v8, v9
	v_cvt_pk_bf16_f32 v53, v10, v11
	v_cvt_pk_bf16_f32 v54, v12, v13
	v_cvt_pk_bf16_f32 v55, v14, v15
	v_cvt_pk_bf16_f32 v56, v16, v17
	v_cvt_pk_bf16_f32 v57, v18, v19
	v_cvt_pk_bf16_f32 v58, v20, v21
	v_cvt_pk_bf16_f32 v59, v22, v23
	v_cvt_pk_bf16_f32 v60, v24, v25
	v_cvt_pk_bf16_f32 v61, v26, v27
	v_cvt_pk_bf16_f32 v62, v28, v29
	v_cvt_pk_bf16_f32 v63, v30, v31
	ds_read_b128 v[112:115], v146 offset:32768
	ds_read_b128 v[116:119], v146 offset:36864
	ds_read_b128 v[120:123], v146 offset:40960
	ds_read_b128 v[124:127], v146 offset:45056
	ds_read_b128 v[128:131], v147 offset:32768
	ds_read_b128 v[132:135], v147 offset:36864
	ds_read_b128 v[136:139], v147 offset:40960
	ds_read_b128 v[140:143], v147 offset:45056
	s_waitcnt lgkmcnt(7)
	v_mfma_f32_16x16x32_bf16 v[32:35], v[112:115], v[48:51], v[32:35]
	ds_read_b128 v[112:115], v148 offset:32768
	s_waitcnt lgkmcnt(7)
	v_mfma_f32_16x16x32_bf16 v[36:39], v[116:119], v[48:51], v[36:39]
	ds_read_b128 v[116:119], v148 offset:36864
	s_waitcnt lgkmcnt(7)
	v_mfma_f32_16x16x32_bf16 v[40:43], v[120:123], v[48:51], v[40:43]
	ds_read_b128 v[120:123], v148 offset:40960
	s_waitcnt lgkmcnt(7)
	v_mfma_f32_16x16x32_bf16 v[44:47], v[124:127], v[48:51], v[44:47]
	ds_read_b128 v[124:127], v148 offset:45056
	s_waitcnt lgkmcnt(7)
	v_mfma_f32_16x16x32_bf16 v[32:35], v[128:131], v[52:55], v[32:35]
	ds_read_b128 v[128:131], v149 offset:32768
	s_waitcnt lgkmcnt(7)
; __device__ __forceinline__ void attn_phase(const Params& P, char* smem_raw) {
;     ...
;       f32x4 sacc[8];
; #pragma unroll
;       for (int t8 = 0; t8 < 8; ++t8) sacc[t8] = f32x4{0.f, 0.f, 0.f, 0.f};
; #pragma unroll
;       for (int s = 0; s < 2; ++s)
; #pragma unroll
;         for (int t8 = 0; t8 < 8; ++t8) {
;           const bf16x8 kf = *reinterpret_cast<const bf16x8*>(&sm_k[(t8 * 16 + (lane_c & 15)) * LDSS + s * 32 + (lane_c >> 4) * 8]);
;           sacc[t8] = __builtin_amdgcn_mfma_f32_16x16x32_bf16(qf[s], kf, sacc[t8], 0, 0, 0);
;         }
;       if (ck < 5) {
;         ATT_ISSUE(t, ck + 1)
;       } else if (t + VGRID < 8192) {
;         ATT_ISSUE(t + VGRID, 0)
;         ATT_QLOAD(t + VGRID)
;       }
;       if (ck < 4) {
;         const float* rb0 = sm_rpb + (rs + ck * 2 - r + 7) * 31;
; #pragma unroll
;         for (int t8 = 0; t8 < 8; ++t8)
; #pragma unroll
;           for (int reg = 0; reg < 4; ++reg)
;             sacc[t8][reg] += rb0[(t8 >> 2) * 31 + dco[reg][t8 & 3]];
;       }
; #pragma unroll
;       for (int reg = 0; reg < 4; ++reg) {
;         float mx = sacc[0][reg];
; #pragma unroll
;         for (int t8 = 1; t8 < 8; ++t8) mx = fmaxf(mx, sacc[t8][reg]);
;         mx = row16_max(mx);
;         const float mnew = fmaxf(mrow[reg], mx);
;         const float alpha = __builtin_amdgcn_exp2f(mrow[reg] - mnew);
;         mrow[reg] = mnew;
;         float rsum = 0.f;
; #pragma unroll
;         for (int t8 = 0; t8 < 8; ++t8) {
;           const float p = __builtin_amdgcn_exp2f(sacc[t8][reg] - mnew);
;           rsum += p;
;           sm_p[(wid * 16 + (lane_c >> 4) * 4 + reg) * 136 + t8 * 16 + (lane_c & 15)] = f2bf(p);
;         }
;         rsum = row16_sum(rsum);
;         lrow[reg] = lrow[reg] * alpha + rsum;
; #pragma unroll
;         for (int td = 0; td < 4; ++td) o[td][reg] *= alpha;
;       }
;       asm volatile("s_waitcnt lgkmcnt(0)" ::: "memory");
; #pragma unroll
;       for (int s4 = 0; s4 < 4; ++s4) {
;         const bf16x8 pf = *reinterpret_cast<const bf16x8*>(&sm_p[(wid * 16 + (lane_c & 15)) * 136 + s4 * 32 + (lane_c >> 4) * 8]);
; #pragma unroll
;         for (int td = 0; td < 4; ++td) {
;           const bf16x8 vf = *reinterpret_cast<const bf16x8*>(&sm_vt[(td * 16 + (lane_c & 15)) * 136 + s4 * 32 + (lane_c >> 4) * 8]);
;           o[td] = __builtin_amdgcn_mfma_f32_16x16x32_bf16(pf, vf, o[td], 0, 0, 0);
;         }
;       }
	v_mfma_f32_16x16x32_bf16 v[36:39], v[132:135], v[52:55], v[36:39]
	ds_read_b128 v[132:135], v149 offset:36864
	s_waitcnt lgkmcnt(7)
	v_mfma_f32_16x16x32_bf16 v[40:43], v[136:139], v[52:55], v[40:43]
	ds_read_b128 v[136:139], v149 offset:40960
	s_waitcnt lgkmcnt(7)
	v_mfma_f32_16x16x32_bf16 v[44:47], v[140:143], v[52:55], v[44:47]
	ds_read_b128 v[140:143], v149 offset:45056
	s_waitcnt lgkmcnt(7)
	v_mfma_f32_16x16x32_bf16 v[32:35], v[112:115], v[56:59], v[32:35]
	s_waitcnt lgkmcnt(6)
	v_mfma_f32_16x16x32_bf16 v[36:39], v[116:119], v[56:59], v[36:39]
	s_waitcnt lgkmcnt(5)
	v_mfma_f32_16x16x32_bf16 v[40:43], v[120:123], v[56:59], v[40:43]
	s_waitcnt lgkmcnt(4)
	v_mfma_f32_16x16x32_bf16 v[44:47], v[124:127], v[56:59], v[44:47]
	s_waitcnt lgkmcnt(3)
	v_mfma_f32_16x16x32_bf16 v[32:35], v[128:131], v[60:63], v[32:35]
	s_waitcnt lgkmcnt(2)
	v_mfma_f32_16x16x32_bf16 v[36:39], v[132:135], v[60:63], v[36:39]
	s_waitcnt lgkmcnt(1)
	v_mfma_f32_16x16x32_bf16 v[40:43], v[136:139], v[60:63], v[40:43]
	s_waitcnt lgkmcnt(0)
	v_mfma_f32_16x16x32_bf16 v[44:47], v[140:143], v[60:63], v[44:47]
	ds_read_b32 v0, v184 offset:896
	ds_read_b32 v1, v185 offset:896
	ds_read_b32 v2, v186 offset:896
	ds_read_b32 v3, v187 offset:896
	ds_read_b32 v4, v188 offset:896
	ds_read_b32 v5, v189 offset:896
	ds_read_b32 v6, v190 offset:896
	ds_read_b32 v7, v191 offset:896
	ds_read_b32 v8, v192 offset:896
	ds_read_b32 v9, v193 offset:896
	ds_read_b32 v10, v194 offset:896
	ds_read_b32 v11, v195 offset:896
	ds_read_b32 v12, v196 offset:896
	ds_read_b32 v13, v197 offset:896
	ds_read_b32 v14, v198 offset:896
	ds_read_b32 v15, v199 offset:896
	ds_read_b32 v16, v184 offset:1024
	ds_read_b32 v17, v185 offset:1024
	ds_read_b32 v18, v186 offset:1024
	ds_read_b32 v19, v187 offset:1024
	ds_read_b32 v20, v188 offset:1024
	ds_read_b32 v21, v189 offset:1024
	ds_read_b32 v22, v190 offset:1024
	ds_read_b32 v23, v191 offset:1024
	ds_read_b32 v24, v192 offset:1024
	ds_read_b32 v25, v193 offset:1024
	ds_read_b32 v26, v194 offset:1024
	ds_read_b32 v27, v195 offset:1024
	ds_read_b32 v28, v196 offset:1024
	ds_read_b32 v29, v197 offset:1024
	ds_read_b32 v30, v198 offset:1024
	ds_read_b32 v31, v199 offset:1024
	s_waitcnt lgkmcnt(0)
	s_barrier
	s_waitcnt vmcnt(0)
	ds_write_b128 v150, v[80:83] offset:32768
	ds_write_b128 v150, v[84:87] offset:36864
	ds_write_b128 v150, v[88:91] offset:40960
	ds_write_b128 v150, v[92:95] offset:45056
	ds_write_b128 v151, v[96:99] offset:32768
	ds_write_b128 v151, v[100:103] offset:36864
	ds_write_b128 v151, v[104:107] offset:40960
	ds_write_b128 v151, v[108:111] offset:45056
	s_add_u32 s100, s16, 0x0
	s_addc_u32 s101, s17, 0
	s_add_u32 s0, s36, 0x0
	s_addc_u32 s1, s37, 0
	global_load_dwordx4 v[80:83], v154, s[100:101] offset:2048
	global_load_dwordx4 v[96:99], v162, s[0:1]
	global_load_dwordx4 v[84:87], v155, s[100:101] offset:2048
	global_load_dwordx4 v[100:103], v163, s[0:1]
	global_load_dwordx4 v[88:91], v156, s[100:101] offset:2048
	global_load_dwordx4 v[104:107], v164, s[0:1]
	global_load_dwordx4 v[92:95], v157, s[100:101] offset:2048
	global_load_dwordx4 v[108:111], v165, s[0:1]
	ds_read_b128 v[112:115], v144 offset:0
	ds_read_b128 v[116:119], v145 offset:0
	ds_read_b128 v[120:123], v144 offset:512
	ds_read_b128 v[124:127], v145 offset:512
	ds_read_b128 v[128:131], v144 offset:4096
	ds_read_b128 v[132:135], v145 offset:4096
	ds_read_b128 v[136:139], v144 offset:4608
	ds_read_b128 v[140:143], v145 offset:4608
	s_waitcnt lgkmcnt(7)
	v_mfma_f32_16x16x32_bf16 v[0:3], v[112:115], v[64:67], v[0:3]
	ds_read_b128 v[112:115], v144 offset:8192
	s_waitcnt lgkmcnt(7)
	v_mfma_f32_16x16x32_bf16 v[0:3], v[116:119], v[68:71], v[0:3]
	ds_read_b128 v[116:119], v145 offset:8192
	s_waitcnt lgkmcnt(7)
	v_mfma_f32_16x16x32_bf16 v[4:7], v[120:123], v[64:67], v[4:7]
	ds_read_b128 v[120:123], v144 offset:8704
	s_waitcnt lgkmcnt(7)
	v_mfma_f32_16x16x32_bf16 v[4:7], v[124:127], v[68:71], v[4:7]
	ds_read_b128 v[124:127], v145 offset:8704
	s_waitcnt lgkmcnt(7)
	v_mfma_f32_16x16x32_bf16 v[8:11], v[128:131], v[64:67], v[8:11]
	ds_read_b128 v[128:131], v144 offset:12288
	s_waitcnt lgkmcnt(7)
	v_mfma_f32_16x16x32_bf16 v[8:11], v[132:135], v[68:71], v[8:11]
	ds_read_b128 v[132:135], v145 offset:12288
	s_waitcnt lgkmcnt(7)
	v_mfma_f32_16x16x32_bf16 v[12:15], v[136:139], v[64:67], v[12:15]
	ds_read_b128 v[136:139], v144 offset:12800
	s_waitcnt lgkmcnt(7)
	v_mfma_f32_16x16x32_bf16 v[12:15], v[140:143], v[68:71], v[12:15]
	ds_read_b128 v[140:143], v145 offset:12800
	s_waitcnt lgkmcnt(7)
	v_mfma_f32_16x16x32_bf16 v[16:19], v[112:115], v[64:67], v[16:19]
	s_waitcnt lgkmcnt(6)
	v_mfma_f32_16x16x32_bf16 v[16:19], v[116:119], v[68:71], v[16:19]
	s_waitcnt lgkmcnt(5)
	v_mfma_f32_16x16x32_bf16 v[20:23], v[120:123], v[64:67], v[20:23]
	s_waitcnt lgkmcnt(4)
	v_mfma_f32_16x16x32_bf16 v[20:23], v[124:127], v[68:71], v[20:23]
	s_waitcnt lgkmcnt(3)
	v_mfma_f32_16x16x32_bf16 v[24:27], v[128:131], v[64:67], v[24:27]
	s_waitcnt lgkmcnt(2)
	v_mfma_f32_16x16x32_bf16 v[24:27], v[132:135], v[68:71], v[24:27]
	s_waitcnt lgkmcnt(1)
	v_mfma_f32_16x16x32_bf16 v[28:31], v[136:139], v[64:67], v[28:31]
	s_waitcnt lgkmcnt(0)
; __device__ __forceinline__ void attn_phase(const Params& P, char* smem_raw) {
;     ...
; #pragma unroll
;       for (int reg = 0; reg < 4; ++reg) {
;         float mx = sacc[0][reg];
; #pragma unroll
;         for (int t8 = 1; t8 < 8; ++t8) mx = fmaxf(mx, sacc[t8][reg]);
;         mx = row16_max(mx);
;         const float mnew = fmaxf(mrow[reg], mx);
;         const float alpha = __builtin_amdgcn_exp2f(mrow[reg] - mnew);
;         mrow[reg] = mnew;
;         float rsum = 0.f;
; #pragma unroll
;         for (int t8 = 0; t8 < 8; ++t8) {
;           const float p = __builtin_amdgcn_exp2f(sacc[t8][reg] - mnew);
;           rsum += p;
;           sm_p[(wid * 16 + (lane_c >> 4) * 4 + reg) * 136 + t8 * 16 + (lane_c & 15)] = f2bf(p);
;         }
;         rsum = row16_sum(rsum);
;         lrow[reg] = lrow[reg] * alpha + rsum;
; #pragma unroll
;         for (int td = 0; td < 4; ++td) o[td][reg] *= alpha;
;       }
;       asm volatile("s_waitcnt lgkmcnt(0)" ::: "memory");
; #pragma unroll
;       for (int s4 = 0; s4 < 4; ++s4) {
;         const bf16x8 pf = *reinterpret_cast<const bf16x8*>(&sm_p[(wid * 16 + (lane_c & 15)) * 136 + s4 * 32 + (lane_c >> 4) * 8]);
; #pragma unroll
;         for (int td = 0; td < 4; ++td) {
;           const bf16x8 vf = *reinterpret_cast<const bf16x8*>(&sm_vt[(td * 16 + (lane_c & 15)) * 136 + s4 * 32 + (lane_c >> 4) * 8]);
;           o[td] = __builtin_amdgcn_mfma_f32_16x16x32_bf16(pf, vf, o[td], 0, 0, 0);
;         }
;       }
	v_mfma_f32_16x16x32_bf16 v[28:31], v[140:143], v[68:71], v[28:31]
	s_nop 7
	v_max3_f32 v203, v0, v1, v2
	v_max3_f32 v203, v203, v3, v4
	v_max3_f32 v203, v203, v5, v6
	v_max3_f32 v203, v203, v7, v8
	v_max3_f32 v203, v203, v9, v10
	v_max3_f32 v203, v203, v11, v12
	v_max3_f32 v203, v203, v13, v14
	v_max3_f32 v203, v203, v15, v16
	v_max3_f32 v203, v203, v17, v18
	v_max3_f32 v203, v203, v19, v20
	v_max3_f32 v203, v203, v21, v22
	v_max3_f32 v203, v203, v23, v24
	v_max3_f32 v203, v203, v25, v26
	v_max3_f32 v203, v203, v27, v28
	v_max3_f32 v203, v203, v29, v30
	v_max_f32_e32 v203, v203, v31
	v_mov_b32_e32 v205, v203
	s_nop 1
	v_permlane16_swap_b32_e32 v203, v205
	v_max_f32_e32 v203, v203, v205
	v_mov_b32_e32 v205, v203
	s_nop 1
	v_permlane32_swap_b32_e32 v203, v205
	v_max_f32_e32 v203, v203, v205
	v_max_f32_e32 v208, v200, v203
	v_sub_f32_e32 v202, v200, v208
	v_exp_f32_e32 v202, v202
	v_mov_b32_e32 v200, v208
	v_sub_f32_e32 v0, v0, v208
	v_sub_f32_e32 v1, v1, v208
	v_sub_f32_e32 v2, v2, v208
	v_sub_f32_e32 v3, v3, v208
	v_sub_f32_e32 v4, v4, v208
	v_sub_f32_e32 v5, v5, v208
	v_sub_f32_e32 v6, v6, v208
	v_sub_f32_e32 v7, v7, v208
	v_sub_f32_e32 v8, v8, v208
	v_sub_f32_e32 v9, v9, v208
	v_sub_f32_e32 v10, v10, v208
	v_sub_f32_e32 v11, v11, v208
	v_sub_f32_e32 v12, v12, v208
	v_sub_f32_e32 v13, v13, v208
	v_sub_f32_e32 v14, v14, v208
	v_sub_f32_e32 v15, v15, v208
	v_sub_f32_e32 v16, v16, v208
	v_sub_f32_e32 v17, v17, v208
	v_sub_f32_e32 v18, v18, v208
	v_sub_f32_e32 v19, v19, v208
	v_sub_f32_e32 v20, v20, v208
	v_sub_f32_e32 v21, v21, v208
	v_sub_f32_e32 v22, v22, v208
	v_sub_f32_e32 v23, v23, v208
	v_sub_f32_e32 v24, v24, v208
	v_sub_f32_e32 v25, v25, v208
	v_sub_f32_e32 v26, v26, v208
	v_sub_f32_e32 v27, v27, v208
	v_sub_f32_e32 v28, v28, v208
	v_sub_f32_e32 v29, v29, v208
	v_sub_f32_e32 v30, v30, v208
	v_sub_f32_e32 v31, v31, v208
	v_exp_f32_e32 v0, v0
	v_exp_f32_e32 v1, v1
	v_exp_f32_e32 v2, v2
	v_exp_f32_e32 v3, v3
	v_exp_f32_e32 v4, v4
	v_exp_f32_e32 v5, v5
	v_exp_f32_e32 v6, v6
	v_exp_f32_e32 v7, v7
	v_exp_f32_e32 v8, v8
	v_exp_f32_e32 v9, v9
	v_exp_f32_e32 v10, v10
	v_exp_f32_e32 v11, v11
	v_exp_f32_e32 v12, v12
	v_exp_f32_e32 v13, v13
	v_exp_f32_e32 v14, v14
	v_exp_f32_e32 v15, v15
	v_exp_f32_e32 v16, v16
	v_exp_f32_e32 v17, v17
	v_exp_f32_e32 v18, v18
	v_exp_f32_e32 v19, v19
	v_exp_f32_e32 v20, v20
	v_exp_f32_e32 v21, v21
	v_exp_f32_e32 v22, v22
	v_exp_f32_e32 v23, v23
	v_exp_f32_e32 v24, v24
	v_exp_f32_e32 v25, v25
	v_exp_f32_e32 v26, v26
	v_exp_f32_e32 v27, v27
	v_exp_f32_e32 v28, v28
	v_exp_f32_e32 v29, v29
	v_exp_f32_e32 v30, v30
	v_exp_f32_e32 v31, v31
	v_mul_f32_e32 v201, v201, v202
	v_mul_f32_e32 v32, v32, v202
	v_mul_f32_e32 v33, v33, v202
	v_mul_f32_e32 v34, v34, v202
	v_mul_f32_e32 v35, v35, v202
	v_mul_f32_e32 v36, v36, v202
	v_mul_f32_e32 v37, v37, v202
	v_mul_f32_e32 v38, v38, v202
	v_mul_f32_e32 v39, v39, v202
	v_mul_f32_e32 v40, v40, v202
	v_mul_f32_e32 v41, v41, v202
	v_mul_f32_e32 v42, v42, v202
	v_mul_f32_e32 v43, v43, v202
	v_mul_f32_e32 v44, v44, v202
	v_mul_f32_e32 v45, v45, v202
	v_mul_f32_e32 v46, v46, v202
	v_mul_f32_e32 v47, v47, v202
	v_add_f32_e32 v203, v0, v1
	v_add_f32_e32 v205, v2, v3
	v_add_f32_e32 v203, v203, v4
	v_add_f32_e32 v205, v205, v5
	v_add_f32_e32 v203, v203, v6
	v_add_f32_e32 v205, v205, v7
	v_add_f32_e32 v203, v203, v8
	v_add_f32_e32 v205, v205, v9
	v_add_f32_e32 v203, v203, v10
	v_add_f32_e32 v205, v205, v11
	v_add_f32_e32 v203, v203, v12
	v_add_f32_e32 v205, v205, v13
	v_add_f32_e32 v203, v203, v14
	v_add_f32_e32 v205, v205, v15
	v_add_f32_e32 v203, v203, v16
	v_add_f32_e32 v205, v205, v17
	v_add_f32_e32 v203, v203, v18
	v_add_f32_e32 v205, v205, v19
	v_add_f32_e32 v203, v203, v20
	v_add_f32_e32 v205, v205, v21
	v_add_f32_e32 v203, v203, v22
	v_add_f32_e32 v205, v205, v23
	v_add_f32_e32 v203, v203, v24
	v_add_f32_e32 v205, v205, v25
	v_add_f32_e32 v203, v203, v26
	v_add_f32_e32 v205, v205, v27
	v_add_f32_e32 v203, v203, v28
	v_add_f32_e32 v205, v205, v29
	v_add_f32_e32 v203, v203, v30
	v_add_f32_e32 v205, v205, v31
	v_add_f32_e32 v203, v203, v205
	v_add_f32_e32 v201, v201, v203
	v_cvt_pk_bf16_f32 v48, v0, v1
	v_cvt_pk_bf16_f32 v49, v2, v3
	v_cvt_pk_bf16_f32 v50, v4, v5
	v_cvt_pk_bf16_f32 v51, v6, v7
	v_cvt_pk_bf16_f32 v52, v8, v9
	v_cvt_pk_bf16_f32 v53, v10, v11
	v_cvt_pk_bf16_f32 v54, v12, v13
	v_cvt_pk_bf16_f32 v55, v14, v15
	v_cvt_pk_bf16_f32 v56, v16, v17
	v_cvt_pk_bf16_f32 v57, v18, v19
	v_cvt_pk_bf16_f32 v58, v20, v21
	v_cvt_pk_bf16_f32 v59, v22, v23
	v_cvt_pk_bf16_f32 v60, v24, v25
	v_cvt_pk_bf16_f32 v61, v26, v27
	v_cvt_pk_bf16_f32 v62, v28, v29
	v_cvt_pk_bf16_f32 v63, v30, v31
	ds_read_b128 v[112:115], v146 offset:0
	ds_read_b128 v[116:119], v146 offset:4096
	ds_read_b128 v[120:123], v146 offset:8192
	ds_read_b128 v[124:127], v146 offset:12288
	ds_read_b128 v[128:131], v147 offset:0
	ds_read_b128 v[132:135], v147 offset:4096
	ds_read_b128 v[136:139], v147 offset:8192
	ds_read_b128 v[140:143], v147 offset:12288
	s_waitcnt lgkmcnt(7)
	v_mfma_f32_16x16x32_bf16 v[32:35], v[112:115], v[48:51], v[32:35]
	ds_read_b128 v[112:115], v148 offset:0
	s_waitcnt lgkmcnt(7)
	v_mfma_f32_16x16x32_bf16 v[36:39], v[116:119], v[48:51], v[36:39]
	ds_read_b128 v[116:119], v148 offset:4096
	s_waitcnt lgkmcnt(7)
	v_mfma_f32_16x16x32_bf16 v[40:43], v[120:123], v[48:51], v[40:43]
	ds_read_b128 v[120:123], v148 offset:8192
	s_waitcnt lgkmcnt(7)
	v_mfma_f32_16x16x32_bf16 v[44:47], v[124:127], v[48:51], v[44:47]
	ds_read_b128 v[124:127], v148 offset:12288
	s_waitcnt lgkmcnt(7)
	v_mfma_f32_16x16x32_bf16 v[32:35], v[128:131], v[52:55], v[32:35]
	ds_read_b128 v[128:131], v149 offset:0
	s_waitcnt lgkmcnt(7)
; __device__ __forceinline__ void attn_phase(const Params& P, char* smem_raw) {
;     ...
;     for (int ck = 0; ck < 6; ++ck) {
;       int lane_c = lane;
;       asm volatile("" : "+v"(lane_c));
;       __syncthreads();
; #pragma unroll
;       for (int i = 0; i < 4; ++i) {
;         const int idx = tid + 256 * i;
;         *reinterpret_cast<uint4*>(&sm_k[(idx >> 3) * LDSS + (idx & 7) * 8]) = kreg[i];
;         *reinterpret_cast<uint4*>(&sm_vt[(idx >> 4) * 136 + (idx & 15) * 8]) = vreg[i];
;       }
;       __syncthreads();
;       f32x4 sacc[8];
; #pragma unroll
;       for (int t8 = 0; t8 < 8; ++t8) sacc[t8] = f32x4{0.f, 0.f, 0.f, 0.f};
; #pragma unroll
;       for (int s = 0; s < 2; ++s)
; #pragma unroll
;         for (int t8 = 0; t8 < 8; ++t8) {
;           const bf16x8 kf = *reinterpret_cast<const bf16x8*>(&sm_k[(t8 * 16 + (lane_c & 15)) * LDSS + s * 32 + (lane_c >> 4) * 8]);
;           sacc[t8] = __builtin_amdgcn_mfma_f32_16x16x32_bf16(qf[s], kf, sacc[t8], 0, 0, 0);
;         }
;       if (ck < 5) {
;         ATT_ISSUE(t, ck + 1)
;       } else if (t + VGRID < 8192) {
;         ATT_ISSUE(t + VGRID, 0)
;         ATT_QLOAD(t + VGRID)
;       }
;       if (ck < 4) {
;         const float* rb0 = sm_rpb + (rs + ck * 2 - r + 7) * 31;
; #pragma unroll
;         for (int t8 = 0; t8 < 8; ++t8)
; #pragma unroll
;           for (int reg = 0; reg < 4; ++reg)
;             sacc[t8][reg] += rb0[(t8 >> 2) * 31 + dco[reg][t8 & 3]];
;       }
	v_mfma_f32_16x16x32_bf16 v[36:39], v[132:135], v[52:55], v[36:39]
	ds_read_b128 v[132:135], v149 offset:4096
	s_waitcnt lgkmcnt(7)
	v_mfma_f32_16x16x32_bf16 v[40:43], v[136:139], v[52:55], v[40:43]
	ds_read_b128 v[136:139], v149 offset:8192
	s_waitcnt lgkmcnt(7)
	v_mfma_f32_16x16x32_bf16 v[44:47], v[140:143], v[52:55], v[44:47]
	ds_read_b128 v[140:143], v149 offset:12288
	s_waitcnt lgkmcnt(7)
	v_mfma_f32_16x16x32_bf16 v[32:35], v[112:115], v[56:59], v[32:35]
	s_waitcnt lgkmcnt(6)
	v_mfma_f32_16x16x32_bf16 v[36:39], v[116:119], v[56:59], v[36:39]
	s_waitcnt lgkmcnt(5)
	v_mfma_f32_16x16x32_bf16 v[40:43], v[120:123], v[56:59], v[40:43]
	s_waitcnt lgkmcnt(4)
	v_mfma_f32_16x16x32_bf16 v[44:47], v[124:127], v[56:59], v[44:47]
	s_waitcnt lgkmcnt(3)
	v_mfma_f32_16x16x32_bf16 v[32:35], v[128:131], v[60:63], v[32:35]
	s_waitcnt lgkmcnt(2)
	v_mfma_f32_16x16x32_bf16 v[36:39], v[132:135], v[60:63], v[36:39]
	s_waitcnt lgkmcnt(1)
	v_mfma_f32_16x16x32_bf16 v[40:43], v[136:139], v[60:63], v[40:43]
	s_waitcnt lgkmcnt(0)
	v_mfma_f32_16x16x32_bf16 v[44:47], v[140:143], v[60:63], v[44:47]
	ds_read_b32 v0, v184 offset:1152
	ds_read_b32 v1, v185 offset:1152
	ds_read_b32 v2, v186 offset:1152
	ds_read_b32 v3, v187 offset:1152
	ds_read_b32 v4, v188 offset:1152
	ds_read_b32 v5, v189 offset:1152
	ds_read_b32 v6, v190 offset:1152
	ds_read_b32 v7, v191 offset:1152
	ds_read_b32 v8, v192 offset:1152
	ds_read_b32 v9, v193 offset:1152
	ds_read_b32 v10, v194 offset:1152
	ds_read_b32 v11, v195 offset:1152
	ds_read_b32 v12, v196 offset:1152
	ds_read_b32 v13, v197 offset:1152
	ds_read_b32 v14, v198 offset:1152
	ds_read_b32 v15, v199 offset:1152
	ds_read_b32 v16, v184 offset:1280
	ds_read_b32 v17, v185 offset:1280
	ds_read_b32 v18, v186 offset:1280
	ds_read_b32 v19, v187 offset:1280
	ds_read_b32 v20, v188 offset:1280
	ds_read_b32 v21, v189 offset:1280
	ds_read_b32 v22, v190 offset:1280
	ds_read_b32 v23, v191 offset:1280
	ds_read_b32 v24, v192 offset:1280
	ds_read_b32 v25, v193 offset:1280
	ds_read_b32 v26, v194 offset:1280
	ds_read_b32 v27, v195 offset:1280
	ds_read_b32 v28, v196 offset:1280
	ds_read_b32 v29, v197 offset:1280
	ds_read_b32 v30, v198 offset:1280
	ds_read_b32 v31, v199 offset:1280
	s_waitcnt lgkmcnt(0)
	s_barrier
	s_waitcnt vmcnt(0)
	ds_write_b128 v150, v[80:83] offset:0
	ds_write_b128 v150, v[84:87] offset:4096
	ds_write_b128 v150, v[88:91] offset:8192
	ds_write_b128 v150, v[92:95] offset:12288
	ds_write_b128 v151, v[96:99] offset:0
	ds_write_b128 v151, v[100:103] offset:4096
	ds_write_b128 v151, v[104:107] offset:8192
	ds_write_b128 v151, v[108:111] offset:12288
	s_add_u32 s100, s16, 0xc0000
	s_addc_u32 s101, s17, 0
	s_add_u32 s0, s36, 0x100
	s_addc_u32 s1, s37, 0
	global_load_dwordx4 v[80:83], v154, s[100:101] offset:2048
	global_load_dwordx4 v[96:99], v162, s[0:1]
	global_load_dwordx4 v[84:87], v155, s[100:101] offset:2048
	global_load_dwordx4 v[100:103], v163, s[0:1]
	global_load_dwordx4 v[88:91], v156, s[100:101] offset:2048
	global_load_dwordx4 v[104:107], v164, s[0:1]
	global_load_dwordx4 v[92:95], v157, s[100:101] offset:2048
	global_load_dwordx4 v[108:111], v165, s[0:1]
	s_and_b32 s0, s3, 0xff
	s_add_u32 s0, s0, 1
	s_min_u32 s0, s0, 15
	s_lshr_b32 s1, s0, 2
	s_and_b32 s0, s0, 3
	s_lshl_b32 s0, s0, 5
	s_lshr_b32 vcc_lo, s3, 12
	s_add_u32 s0, s0, vcc_lo
	s_sub_i32 vcc_lo, s0, 4
	s_max_i32 vcc_lo, vcc_lo, 0
	s_min_i32 vcc_lo, vcc_lo, 0x78
	s_lshl_b32 vcc_hi, s1, 13
	s_lshl_b32 m0, vcc_lo, 6
	s_add_u32 m0, m0, vcc_hi
	s_mul_i32 m0, m0, 0x1800
	s_add_u32 s12, s4, m0
	s_addc_u32 s13, s5, 0
	s_lshl_b32 m0, s1, 24
	s_lshl_b32 s100, vcc_lo, 7
	s_add_u32 m0, m0, s100
	s_add_u32 s14, s6, m0
	s_addc_u32 s15, s7, 0
	s_lshl_b32 m0, s0, 6
	s_add_u32 m0, m0, vcc_hi
	s_mul_i32 m0, m0, 0x1800
	s_add_u32 s100, s4, m0
	s_addc_u32 s101, s5, 0
	global_load_dwordx4 v[72:75], v166, s[100:101]
	global_load_dwordx4 v[76:79], v166, s[100:101] offset:64
	ds_read_b128 v[112:115], v144 offset:32768
	ds_read_b128 v[116:119], v145 offset:32768
	ds_read_b128 v[120:123], v144 offset:33280
	ds_read_b128 v[124:127], v145 offset:33280
	ds_read_b128 v[128:131], v144 offset:36864
	ds_read_b128 v[132:135], v145 offset:36864
	ds_read_b128 v[136:139], v144 offset:37376
	ds_read_b128 v[140:143], v145 offset:37376
	s_waitcnt lgkmcnt(7)
	v_mfma_f32_16x16x32_bf16 v[0:3], v[112:115], v[64:67], v[0:3]
	ds_read_b128 v[112:115], v144 offset:40960
	s_waitcnt lgkmcnt(7)
	v_mfma_f32_16x16x32_bf16 v[0:3], v[116:119], v[68:71], v[0:3]
	ds_read_b128 v[116:119], v145 offset:40960
	s_waitcnt lgkmcnt(7)
	v_mfma_f32_16x16x32_bf16 v[4:7], v[120:123], v[64:67], v[4:7]
	ds_read_b128 v[120:123], v144 offset:41472
	s_waitcnt lgkmcnt(7)
	v_mfma_f32_16x16x32_bf16 v[4:7], v[124:127], v[68:71], v[4:7]
	ds_read_b128 v[124:127], v145 offset:41472
	s_waitcnt lgkmcnt(7)
	v_mfma_f32_16x16x32_bf16 v[8:11], v[128:131], v[64:67], v[8:11]
	ds_read_b128 v[128:131], v144 offset:45056
	s_waitcnt lgkmcnt(7)
	v_mfma_f32_16x16x32_bf16 v[8:11], v[132:135], v[68:71], v[8:11]
	ds_read_b128 v[132:135], v145 offset:45056
	s_waitcnt lgkmcnt(7)
	v_mfma_f32_16x16x32_bf16 v[12:15], v[136:139], v[64:67], v[12:15]
	ds_read_b128 v[136:139], v144 offset:45568
	s_waitcnt lgkmcnt(7)
	v_mfma_f32_16x16x32_bf16 v[12:15], v[140:143], v[68:71], v[12:15]
	ds_read_b128 v[140:143], v145 offset:45568
	s_waitcnt lgkmcnt(7)
	v_mfma_f32_16x16x32_bf16 v[16:19], v[112:115], v[64:67], v[16:19]
	s_waitcnt lgkmcnt(6)
	v_mfma_f32_16x16x32_bf16 v[16:19], v[116:119], v[68:71], v[16:19]
	s_waitcnt lgkmcnt(5)
	v_mfma_f32_16x16x32_bf16 v[20:23], v[120:123], v[64:67], v[20:23]
	s_waitcnt lgkmcnt(4)
	v_mfma_f32_16x16x32_bf16 v[20:23], v[124:127], v[68:71], v[20:23]
	s_waitcnt lgkmcnt(3)
; __device__ __forceinline__ void attn_phase(const Params& P, char* smem_raw) {
;     ...
; #pragma unroll
;       for (int reg = 0; reg < 4; ++reg) {
;         float mx = sacc[0][reg];
; #pragma unroll
;         for (int t8 = 1; t8 < 8; ++t8) mx = fmaxf(mx, sacc[t8][reg]);
;         mx = row16_max(mx);
;         const float mnew = fmaxf(mrow[reg], mx);
;         const float alpha = __builtin_amdgcn_exp2f(mrow[reg] - mnew);
;         mrow[reg] = mnew;
;         float rsum = 0.f;
; #pragma unroll
;         for (int t8 = 0; t8 < 8; ++t8) {
;           const float p = __builtin_amdgcn_exp2f(sacc[t8][reg] - mnew);
;           rsum += p;
;           sm_p[(wid * 16 + (lane_c >> 4) * 4 + reg) * 136 + t8 * 16 + (lane_c & 15)] = f2bf(p);
;         }
;         rsum = row16_sum(rsum);
;         lrow[reg] = lrow[reg] * alpha + rsum;
; #pragma unroll
;         for (int td = 0; td < 4; ++td) o[td][reg] *= alpha;
;       }
;       asm volatile("s_waitcnt lgkmcnt(0)" ::: "memory");
; #pragma unroll
;       for (int s4 = 0; s4 < 4; ++s4) {
;         const bf16x8 pf = *reinterpret_cast<const bf16x8*>(&sm_p[(wid * 16 + (lane_c & 15)) * 136 + s4 * 32 + (lane_c >> 4) * 8]);
; #pragma unroll
;         for (int td = 0; td < 4; ++td) {
;           const bf16x8 vf = *reinterpret_cast<const bf16x8*>(&sm_vt[(td * 16 + (lane_c & 15)) * 136 + s4 * 32 + (lane_c >> 4) * 8]);
;           o[td] = __builtin_amdgcn_mfma_f32_16x16x32_bf16(pf, vf, o[td], 0, 0, 0);
;         }
;       }
	v_mfma_f32_16x16x32_bf16 v[24:27], v[128:131], v[64:67], v[24:27]
	s_waitcnt lgkmcnt(2)
	v_mfma_f32_16x16x32_bf16 v[24:27], v[132:135], v[68:71], v[24:27]
	s_waitcnt lgkmcnt(1)
	v_mfma_f32_16x16x32_bf16 v[28:31], v[136:139], v[64:67], v[28:31]
	s_waitcnt lgkmcnt(0)
	v_mfma_f32_16x16x32_bf16 v[28:31], v[140:143], v[68:71], v[28:31]
	s_nop 7
	v_max3_f32 v203, v0, v1, v2
	v_max3_f32 v203, v203, v3, v4
	v_max3_f32 v203, v203, v5, v6
	v_max3_f32 v203, v203, v7, v8
	v_max3_f32 v203, v203, v9, v10
	v_max3_f32 v203, v203, v11, v12
	v_max3_f32 v203, v203, v13, v14
	v_max3_f32 v203, v203, v15, v16
	v_max3_f32 v203, v203, v17, v18
	v_max3_f32 v203, v203, v19, v20
	v_max3_f32 v203, v203, v21, v22
	v_max3_f32 v203, v203, v23, v24
	v_max3_f32 v203, v203, v25, v26
	v_max3_f32 v203, v203, v27, v28
	v_max3_f32 v203, v203, v29, v30
	v_max_f32_e32 v203, v203, v31
	v_mov_b32_e32 v205, v203
	s_nop 1
	v_permlane16_swap_b32_e32 v203, v205
	v_max_f32_e32 v203, v203, v205
	v_mov_b32_e32 v205, v203
	s_nop 1
	v_permlane32_swap_b32_e32 v203, v205
	v_max_f32_e32 v203, v203, v205
	v_max_f32_e32 v208, v200, v203
	v_sub_f32_e32 v202, v200, v208
	v_exp_f32_e32 v202, v202
	v_mov_b32_e32 v200, v208
	v_sub_f32_e32 v0, v0, v208
	v_sub_f32_e32 v1, v1, v208
	v_sub_f32_e32 v2, v2, v208
	v_sub_f32_e32 v3, v3, v208
	v_sub_f32_e32 v4, v4, v208
	v_sub_f32_e32 v5, v5, v208
	v_sub_f32_e32 v6, v6, v208
	v_sub_f32_e32 v7, v7, v208
	v_sub_f32_e32 v8, v8, v208
	v_sub_f32_e32 v9, v9, v208
	v_sub_f32_e32 v10, v10, v208
	v_sub_f32_e32 v11, v11, v208
	v_sub_f32_e32 v12, v12, v208
	v_sub_f32_e32 v13, v13, v208
	v_sub_f32_e32 v14, v14, v208
	v_sub_f32_e32 v15, v15, v208
	v_sub_f32_e32 v16, v16, v208
	v_sub_f32_e32 v17, v17, v208
	v_sub_f32_e32 v18, v18, v208
	v_sub_f32_e32 v19, v19, v208
	v_sub_f32_e32 v20, v20, v208
	v_sub_f32_e32 v21, v21, v208
	v_sub_f32_e32 v22, v22, v208
	v_sub_f32_e32 v23, v23, v208
	v_sub_f32_e32 v24, v24, v208
	v_sub_f32_e32 v25, v25, v208
	v_sub_f32_e32 v26, v26, v208
	v_sub_f32_e32 v27, v27, v208
	v_sub_f32_e32 v28, v28, v208
	v_sub_f32_e32 v29, v29, v208
	v_sub_f32_e32 v30, v30, v208
	v_sub_f32_e32 v31, v31, v208
	v_exp_f32_e32 v0, v0
	v_exp_f32_e32 v1, v1
	v_exp_f32_e32 v2, v2
	v_exp_f32_e32 v3, v3
	v_exp_f32_e32 v4, v4
	v_exp_f32_e32 v5, v5
	v_exp_f32_e32 v6, v6
	v_exp_f32_e32 v7, v7
	v_exp_f32_e32 v8, v8
	v_exp_f32_e32 v9, v9
	v_exp_f32_e32 v10, v10
	v_exp_f32_e32 v11, v11
	v_exp_f32_e32 v12, v12
	v_exp_f32_e32 v13, v13
	v_exp_f32_e32 v14, v14
	v_exp_f32_e32 v15, v15
	v_exp_f32_e32 v16, v16
	v_exp_f32_e32 v17, v17
	v_exp_f32_e32 v18, v18
	v_exp_f32_e32 v19, v19
	v_exp_f32_e32 v20, v20
	v_exp_f32_e32 v21, v21
	v_exp_f32_e32 v22, v22
	v_exp_f32_e32 v23, v23
	v_exp_f32_e32 v24, v24
	v_exp_f32_e32 v25, v25
	v_exp_f32_e32 v26, v26
	v_exp_f32_e32 v27, v27
	v_exp_f32_e32 v28, v28
	v_exp_f32_e32 v29, v29
	v_exp_f32_e32 v30, v30
	v_exp_f32_e32 v31, v31
	v_mul_f32_e32 v201, v201, v202
	v_mul_f32_e32 v32, v32, v202
	v_mul_f32_e32 v33, v33, v202
	v_mul_f32_e32 v34, v34, v202
	v_mul_f32_e32 v35, v35, v202
	v_mul_f32_e32 v36, v36, v202
	v_mul_f32_e32 v37, v37, v202
	v_mul_f32_e32 v38, v38, v202
	v_mul_f32_e32 v39, v39, v202
	v_mul_f32_e32 v40, v40, v202
	v_mul_f32_e32 v41, v41, v202
	v_mul_f32_e32 v42, v42, v202
	v_mul_f32_e32 v43, v43, v202
	v_mul_f32_e32 v44, v44, v202
	v_mul_f32_e32 v45, v45, v202
	v_mul_f32_e32 v46, v46, v202
	v_mul_f32_e32 v47, v47, v202
	v_add_f32_e32 v203, v0, v1
	v_add_f32_e32 v205, v2, v3
	v_add_f32_e32 v203, v203, v4
	v_add_f32_e32 v205, v205, v5
	v_add_f32_e32 v203, v203, v6
	v_add_f32_e32 v205, v205, v7
	v_add_f32_e32 v203, v203, v8
	v_add_f32_e32 v205, v205, v9
	v_add_f32_e32 v203, v203, v10
	v_add_f32_e32 v205, v205, v11
	v_add_f32_e32 v203, v203, v12
	v_add_f32_e32 v205, v205, v13
	v_add_f32_e32 v203, v203, v14
	v_add_f32_e32 v205, v205, v15
	v_add_f32_e32 v203, v203, v16
	v_add_f32_e32 v205, v205, v17
	v_add_f32_e32 v203, v203, v18
	v_add_f32_e32 v205, v205, v19
	v_add_f32_e32 v203, v203, v20
	v_add_f32_e32 v205, v205, v21
	v_add_f32_e32 v203, v203, v22
	v_add_f32_e32 v205, v205, v23
	v_add_f32_e32 v203, v203, v24
	v_add_f32_e32 v205, v205, v25
	v_add_f32_e32 v203, v203, v26
	v_add_f32_e32 v205, v205, v27
	v_add_f32_e32 v203, v203, v28
	v_add_f32_e32 v205, v205, v29
	v_add_f32_e32 v203, v203, v30
	v_add_f32_e32 v205, v205, v31
	v_add_f32_e32 v203, v203, v205
	v_add_f32_e32 v201, v201, v203
	v_cvt_pk_bf16_f32 v48, v0, v1
	v_cvt_pk_bf16_f32 v49, v2, v3
	v_cvt_pk_bf16_f32 v50, v4, v5
	v_cvt_pk_bf16_f32 v51, v6, v7
	v_cvt_pk_bf16_f32 v52, v8, v9
	v_cvt_pk_bf16_f32 v53, v10, v11
	v_cvt_pk_bf16_f32 v54, v12, v13
	v_cvt_pk_bf16_f32 v55, v14, v15
	v_cvt_pk_bf16_f32 v56, v16, v17
	v_cvt_pk_bf16_f32 v57, v18, v19
	v_cvt_pk_bf16_f32 v58, v20, v21
	v_cvt_pk_bf16_f32 v59, v22, v23
	v_cvt_pk_bf16_f32 v60, v24, v25
	v_cvt_pk_bf16_f32 v61, v26, v27
	v_cvt_pk_bf16_f32 v62, v28, v29
	v_cvt_pk_bf16_f32 v63, v30, v31
	ds_read_b128 v[112:115], v146 offset:32768
	ds_read_b128 v[116:119], v146 offset:36864
	ds_read_b128 v[120:123], v146 offset:40960
	ds_read_b128 v[124:127], v146 offset:45056
	ds_read_b128 v[128:131], v147 offset:32768
	ds_read_b128 v[132:135], v147 offset:36864
	ds_read_b128 v[136:139], v147 offset:40960
	ds_read_b128 v[140:143], v147 offset:45056
	s_waitcnt lgkmcnt(7)
	v_mfma_f32_16x16x32_bf16 v[32:35], v[112:115], v[48:51], v[32:35]
	ds_read_b128 v[112:115], v148 offset:32768
	s_waitcnt lgkmcnt(7)
	v_mfma_f32_16x16x32_bf16 v[36:39], v[116:119], v[48:51], v[36:39]
	ds_read_b128 v[116:119], v148 offset:36864
	s_waitcnt lgkmcnt(7)
	v_mfma_f32_16x16x32_bf16 v[40:43], v[120:123], v[48:51], v[40:43]
	ds_read_b128 v[120:123], v148 offset:40960
	s_waitcnt lgkmcnt(7)
	v_mfma_f32_16x16x32_bf16 v[44:47], v[124:127], v[48:51], v[44:47]
	ds_read_b128 v[124:127], v148 offset:45056
	s_waitcnt lgkmcnt(7)
	v_mfma_f32_16x16x32_bf16 v[32:35], v[128:131], v[52:55], v[32:35]
	ds_read_b128 v[128:131], v149 offset:32768
	s_waitcnt lgkmcnt(7)
	v_mfma_f32_16x16x32_bf16 v[36:39], v[132:135], v[52:55], v[36:39]
	ds_read_b128 v[132:135], v149 offset:36864
	s_waitcnt lgkmcnt(7)
	v_mfma_f32_16x16x32_bf16 v[40:43], v[136:139], v[52:55], v[40:43]
	ds_read_b128 v[136:139], v149 offset:40960
	s_waitcnt lgkmcnt(7)
	v_mfma_f32_16x16x32_bf16 v[44:47], v[140:143], v[52:55], v[44:47]
	ds_read_b128 v[140:143], v149 offset:45056
	s_waitcnt lgkmcnt(7)
	v_mfma_f32_16x16x32_bf16 v[32:35], v[112:115], v[56:59], v[32:35]
	s_waitcnt lgkmcnt(6)
	v_mfma_f32_16x16x32_bf16 v[36:39], v[116:119], v[56:59], v[36:39]
	s_waitcnt lgkmcnt(5)
	v_mfma_f32_16x16x32_bf16 v[40:43], v[120:123], v[56:59], v[40:43]
	s_waitcnt lgkmcnt(4)
	v_mfma_f32_16x16x32_bf16 v[44:47], v[124:127], v[56:59], v[44:47]
	s_waitcnt lgkmcnt(3)
	v_mfma_f32_16x16x32_bf16 v[32:35], v[128:131], v[60:63], v[32:35]
	s_waitcnt lgkmcnt(2)
	v_mfma_f32_16x16x32_bf16 v[36:39], v[132:135], v[60:63], v[36:39]
	s_waitcnt lgkmcnt(1)
	v_mfma_f32_16x16x32_bf16 v[40:43], v[136:139], v[60:63], v[40:43]
	s_waitcnt lgkmcnt(0)
	v_mfma_f32_16x16x32_bf16 v[44:47], v[140:143], v[60:63], v[44:47]
	s_waitcnt lgkmcnt(0)
	s_barrier
; __device__ __forceinline__ void attn_phase(const Params& P, char* smem_raw) {
;     ...
;     for (int ck = 0; ck < 6; ++ck) {
;       int lane_c = lane;
;       asm volatile("" : "+v"(lane_c));
;       __syncthreads();
; #pragma unroll
;       for (int i = 0; i < 4; ++i) {
;         const int idx = tid + 256 * i;
;         *reinterpret_cast<uint4*>(&sm_k[(idx >> 3) * LDSS + (idx & 7) * 8]) = kreg[i];
;         *reinterpret_cast<uint4*>(&sm_vt[(idx >> 4) * 136 + (idx & 15) * 8]) = vreg[i];
;       }
;       __syncthreads();
;       f32x4 sacc[8];
; #pragma unroll
;       for (int t8 = 0; t8 < 8; ++t8) sacc[t8] = f32x4{0.f, 0.f, 0.f, 0.f};
; #pragma unroll
;       for (int s = 0; s < 2; ++s)
; #pragma unroll
;         for (int t8 = 0; t8 < 8; ++t8) {
;           const bf16x8 kf = *reinterpret_cast<const bf16x8*>(&sm_k[(t8 * 16 + (lane_c & 15)) * LDSS + s * 32 + (lane_c >> 4) * 8]);
;           sacc[t8] = __builtin_amdgcn_mfma_f32_16x16x32_bf16(qf[s], kf, sacc[t8], 0, 0, 0);
;         }
;       if (ck < 5) {
;         ATT_ISSUE(t, ck + 1)
;       } else if (t + VGRID < 8192) {
;         ATT_ISSUE(t + VGRID, 0)
;         ATT_QLOAD(t + VGRID)
;       }
;       if (ck < 4) {
;         const float* rb0 = sm_rpb + (rs + ck * 2 - r + 7) * 31;
; #pragma unroll
;         for (int t8 = 0; t8 < 8; ++t8)
; #pragma unroll
;           for (int reg = 0; reg < 4; ++reg)
;             sacc[t8][reg] += rb0[(t8 >> 2) * 31 + dco[reg][t8 & 3]];
;       }
; #pragma unroll
;       for (int reg = 0; reg < 4; ++reg) {
;         float mx = sacc[0][reg];
; #pragma unroll
;         for (int t8 = 1; t8 < 8; ++t8) mx = fmaxf(mx, sacc[t8][reg]);
;         mx = row16_max(mx);
;         const float mnew = fmaxf(mrow[reg], mx);
;         const float alpha = __builtin_amdgcn_exp2f(mrow[reg] - mnew);
;         mrow[reg] = mnew;
;         float rsum = 0.f;
; #pragma unroll
;         for (int t8 = 0; t8 < 8; ++t8) {
;           const float p = __builtin_amdgcn_exp2f(sacc[t8][reg] - mnew);
	s_waitcnt vmcnt(2)
	ds_write_b128 v150, v[80:83] offset:32768
	ds_write_b128 v150, v[84:87] offset:36864
	ds_write_b128 v150, v[88:91] offset:40960
	ds_write_b128 v150, v[92:95] offset:45056
	ds_write_b128 v151, v[96:99] offset:32768
	ds_write_b128 v151, v[100:103] offset:36864
	ds_write_b128 v151, v[104:107] offset:40960
	ds_write_b128 v151, v[108:111] offset:45056
	s_add_u32 s100, s12, 0x0
	s_addc_u32 s101, s13, 0
	s_add_u32 s0, s14, 0x0
	s_addc_u32 s1, s15, 0
	global_load_dwordx4 v[80:83], v154, s[100:101] offset:2048
	global_load_dwordx4 v[96:99], v158, s[0:1]
	global_load_dwordx4 v[84:87], v155, s[100:101] offset:2048
	global_load_dwordx4 v[100:103], v159, s[0:1]
	global_load_dwordx4 v[88:91], v156, s[100:101] offset:2048
	global_load_dwordx4 v[104:107], v160, s[0:1]
	global_load_dwordx4 v[92:95], v157, s[100:101] offset:2048
	global_load_dwordx4 v[108:111], v161, s[0:1]
	s_and_b32 s0, s3, 0xff
	s_add_u32 s0, s0, 1
	s_min_u32 s0, s0, 15
	s_lshr_b32 s1, s0, 2
	s_and_b32 s0, s0, 3
	s_lshl_b32 s0, s0, 5
	s_lshr_b32 vcc_lo, s3, 12
	s_add_u32 s0, s0, vcc_lo
	s_sub_i32 vcc_lo, s0, 4
	s_max_i32 vcc_lo, vcc_lo, 0
	s_min_i32 vcc_lo, vcc_lo, 0x78
	s_lshl_b32 vcc_hi, s1, 13
	s_sub_i32 vcc_lo, vcc_lo, s0
	s_add_i32 vcc_lo, vcc_lo, 4
	s_lshl_b32 vcc_lo, vcc_lo, 7
	s_bfe_u32 m0, s3, 0x10008
	s_mul_i32 m0, m0, 0x12000
	s_add_i32 vcc_lo, vcc_lo, m0
	s_add_i32 vcc_lo, vcc_lo, 0x10010
	v_add_u32_e32 v184, vcc_lo, v168
	v_add_u32_e32 v185, vcc_lo, v169
	v_add_u32_e32 v186, vcc_lo, v170
	v_add_u32_e32 v187, vcc_lo, v171
	v_add_u32_e32 v188, vcc_lo, v172
	v_add_u32_e32 v189, vcc_lo, v173
	v_add_u32_e32 v190, vcc_lo, v174
	v_add_u32_e32 v191, vcc_lo, v175
	v_add_u32_e32 v192, vcc_lo, v176
	v_add_u32_e32 v193, vcc_lo, v177
	v_add_u32_e32 v194, vcc_lo, v178
	v_add_u32_e32 v195, vcc_lo, v179
	v_add_u32_e32 v196, vcc_lo, v180
	v_add_u32_e32 v197, vcc_lo, v181
	v_add_u32_e32 v198, vcc_lo, v182
	v_add_u32_e32 v199, vcc_lo, v183
	ds_read_b128 v[112:115], v144 offset:0
	ds_read_b128 v[116:119], v145 offset:0
	ds_read_b128 v[120:123], v144 offset:512
	ds_read_b128 v[124:127], v145 offset:512
	ds_read_b128 v[128:131], v144 offset:4096
	ds_read_b128 v[132:135], v145 offset:4096
	ds_read_b128 v[136:139], v144 offset:4608
	ds_read_b128 v[140:143], v145 offset:4608
	s_waitcnt lgkmcnt(7)
	v_mfma_f32_16x16x32_bf16 v[0:3], v[112:115], v[64:67], 0
	ds_read_b128 v[112:115], v144 offset:8192
	s_waitcnt lgkmcnt(7)
	v_mfma_f32_16x16x32_bf16 v[0:3], v[116:119], v[68:71], v[0:3]
	ds_read_b128 v[116:119], v145 offset:8192
	s_waitcnt lgkmcnt(7)
	v_mfma_f32_16x16x32_bf16 v[4:7], v[120:123], v[64:67], 0
	ds_read_b128 v[120:123], v144 offset:8704
	s_waitcnt lgkmcnt(7)
	v_mfma_f32_16x16x32_bf16 v[4:7], v[124:127], v[68:71], v[4:7]
	ds_read_b128 v[124:127], v145 offset:8704
	s_waitcnt lgkmcnt(7)
	v_mfma_f32_16x16x32_bf16 v[8:11], v[128:131], v[64:67], 0
	ds_read_b128 v[128:131], v144 offset:12288
	s_waitcnt lgkmcnt(7)
	v_mfma_f32_16x16x32_bf16 v[8:11], v[132:135], v[68:71], v[8:11]
	ds_read_b128 v[132:135], v145 offset:12288
	s_waitcnt lgkmcnt(7)
	v_mfma_f32_16x16x32_bf16 v[12:15], v[136:139], v[64:67], 0
	ds_read_b128 v[136:139], v144 offset:12800
	s_waitcnt lgkmcnt(7)
	v_mfma_f32_16x16x32_bf16 v[12:15], v[140:143], v[68:71], v[12:15]
	ds_read_b128 v[140:143], v145 offset:12800
	s_waitcnt lgkmcnt(7)
	v_mfma_f32_16x16x32_bf16 v[16:19], v[112:115], v[64:67], 0
	s_waitcnt lgkmcnt(6)
	v_mfma_f32_16x16x32_bf16 v[16:19], v[116:119], v[68:71], v[16:19]
	s_waitcnt lgkmcnt(5)
	v_mfma_f32_16x16x32_bf16 v[20:23], v[120:123], v[64:67], 0
	s_waitcnt lgkmcnt(4)
	v_mfma_f32_16x16x32_bf16 v[20:23], v[124:127], v[68:71], v[20:23]
	s_waitcnt lgkmcnt(3)
	v_mfma_f32_16x16x32_bf16 v[24:27], v[128:131], v[64:67], 0
	s_waitcnt lgkmcnt(2)
	v_mfma_f32_16x16x32_bf16 v[24:27], v[132:135], v[68:71], v[24:27]
	s_waitcnt lgkmcnt(1)
	v_mfma_f32_16x16x32_bf16 v[28:31], v[136:139], v[64:67], 0
	s_waitcnt lgkmcnt(0)
	v_mfma_f32_16x16x32_bf16 v[28:31], v[140:143], v[68:71], v[28:31]
	s_nop 7
	v_max3_f32 v203, v0, v1, v2
	v_max3_f32 v203, v203, v3, v4
	v_max3_f32 v203, v203, v5, v6
	v_max3_f32 v203, v203, v7, v8
	v_max3_f32 v203, v203, v9, v10
	v_max3_f32 v203, v203, v11, v12
	v_max3_f32 v203, v203, v13, v14
	v_max3_f32 v203, v203, v15, v16
	v_max3_f32 v203, v203, v17, v18
	v_max3_f32 v203, v203, v19, v20
	v_max3_f32 v203, v203, v21, v22
	v_max3_f32 v203, v203, v23, v24
	v_max3_f32 v203, v203, v25, v26
	v_max3_f32 v203, v203, v27, v28
	v_max3_f32 v203, v203, v29, v30
	v_max_f32_e32 v203, v203, v31
	v_mov_b32_e32 v205, v203
	s_nop 1
	v_permlane16_swap_b32_e32 v203, v205
	v_max_f32_e32 v203, v203, v205
	v_mov_b32_e32 v205, v203
	s_nop 1
	v_permlane32_swap_b32_e32 v203, v205
	v_max_f32_e32 v203, v203, v205
	v_max_f32_e32 v208, v200, v203
	v_sub_f32_e32 v202, v200, v208
	v_exp_f32_e32 v202, v202
	v_mov_b32_e32 v200, v208
	v_sub_f32_e32 v0, v0, v208
	v_sub_f32_e32 v1, v1, v208
	v_sub_f32_e32 v2, v2, v208
	v_sub_f32_e32 v3, v3, v208
	v_sub_f32_e32 v4, v4, v208
	v_sub_f32_e32 v5, v5, v208
	v_sub_f32_e32 v6, v6, v208
	v_sub_f32_e32 v7, v7, v208
	v_sub_f32_e32 v8, v8, v208
	v_sub_f32_e32 v9, v9, v208
	v_sub_f32_e32 v10, v10, v208
	v_sub_f32_e32 v11, v11, v208
	v_sub_f32_e32 v12, v12, v208
	v_sub_f32_e32 v13, v13, v208
	v_sub_f32_e32 v14, v14, v208
	v_sub_f32_e32 v15, v15, v208
	v_sub_f32_e32 v16, v16, v208
	v_sub_f32_e32 v17, v17, v208
	v_sub_f32_e32 v18, v18, v208
	v_sub_f32_e32 v19, v19, v208
	v_sub_f32_e32 v20, v20, v208
	v_sub_f32_e32 v21, v21, v208
	v_sub_f32_e32 v22, v22, v208
	v_sub_f32_e32 v23, v23, v208
	v_sub_f32_e32 v24, v24, v208
	v_sub_f32_e32 v25, v25, v208
	v_sub_f32_e32 v26, v26, v208
	v_sub_f32_e32 v27, v27, v208
; __device__ __forceinline__ void attn_phase(const Params& P, char* smem_raw) {
;     ...
;         float rsum = 0.f;
; #pragma unroll
;         for (int t8 = 0; t8 < 8; ++t8) {
;           const float p = __builtin_amdgcn_exp2f(sacc[t8][reg] - mnew);
;           rsum += p;
;           sm_p[(wid * 16 + (lane_c >> 4) * 4 + reg) * 136 + t8 * 16 + (lane_c & 15)] = f2bf(p);
;         }
;         rsum = row16_sum(rsum);
;         lrow[reg] = lrow[reg] * alpha + rsum;
; #pragma unroll
;         for (int td = 0; td < 4; ++td) o[td][reg] *= alpha;
;       }
;       asm volatile("s_waitcnt lgkmcnt(0)" ::: "memory");
; #pragma unroll
;       for (int s4 = 0; s4 < 4; ++s4) {
;         const bf16x8 pf = *reinterpret_cast<const bf16x8*>(&sm_p[(wid * 16 + (lane_c & 15)) * 136 + s4 * 32 + (lane_c >> 4) * 8]);
; #pragma unroll
;         for (int td = 0; td < 4; ++td) {
;           const bf16x8 vf = *reinterpret_cast<const bf16x8*>(&sm_vt[(td * 16 + (lane_c & 15)) * 136 + s4 * 32 + (lane_c >> 4) * 8]);
;           o[td] = __builtin_amdgcn_mfma_f32_16x16x32_bf16(pf, vf, o[td], 0, 0, 0);
;         }
;       }
	v_sub_f32_e32 v28, v28, v208
	v_sub_f32_e32 v29, v29, v208
	v_sub_f32_e32 v30, v30, v208
	v_sub_f32_e32 v31, v31, v208
	v_exp_f32_e32 v0, v0
	v_exp_f32_e32 v1, v1
	v_exp_f32_e32 v2, v2
	v_exp_f32_e32 v3, v3
	v_exp_f32_e32 v4, v4
	v_exp_f32_e32 v5, v5
	v_exp_f32_e32 v6, v6
	v_exp_f32_e32 v7, v7
	v_exp_f32_e32 v8, v8
	v_exp_f32_e32 v9, v9
	v_exp_f32_e32 v10, v10
	v_exp_f32_e32 v11, v11
	v_exp_f32_e32 v12, v12
	v_exp_f32_e32 v13, v13
	v_exp_f32_e32 v14, v14
	v_exp_f32_e32 v15, v15
	v_exp_f32_e32 v16, v16
	v_exp_f32_e32 v17, v17
	v_exp_f32_e32 v18, v18
	v_exp_f32_e32 v19, v19
	v_exp_f32_e32 v20, v20
	v_exp_f32_e32 v21, v21
	v_exp_f32_e32 v22, v22
	v_exp_f32_e32 v23, v23
	v_exp_f32_e32 v24, v24
	v_exp_f32_e32 v25, v25
	v_exp_f32_e32 v26, v26
	v_exp_f32_e32 v27, v27
	v_exp_f32_e32 v28, v28
	v_exp_f32_e32 v29, v29
	v_exp_f32_e32 v30, v30
	v_exp_f32_e32 v31, v31
	v_mul_f32_e32 v201, v201, v202
	v_mul_f32_e32 v32, v32, v202
	v_mul_f32_e32 v33, v33, v202
	v_mul_f32_e32 v34, v34, v202
	v_mul_f32_e32 v35, v35, v202
	v_mul_f32_e32 v36, v36, v202
	v_mul_f32_e32 v37, v37, v202
	v_mul_f32_e32 v38, v38, v202
	v_mul_f32_e32 v39, v39, v202
	v_mul_f32_e32 v40, v40, v202
	v_mul_f32_e32 v41, v41, v202
	v_mul_f32_e32 v42, v42, v202
	v_mul_f32_e32 v43, v43, v202
	v_mul_f32_e32 v44, v44, v202
	v_mul_f32_e32 v45, v45, v202
	v_mul_f32_e32 v46, v46, v202
	v_mul_f32_e32 v47, v47, v202
	v_add_f32_e32 v203, v0, v1
	v_add_f32_e32 v205, v2, v3
	v_add_f32_e32 v203, v203, v4
	v_add_f32_e32 v205, v205, v5
	v_add_f32_e32 v203, v203, v6
	v_add_f32_e32 v205, v205, v7
	v_add_f32_e32 v203, v203, v8
	v_add_f32_e32 v205, v205, v9
	v_add_f32_e32 v203, v203, v10
	v_add_f32_e32 v205, v205, v11
	v_add_f32_e32 v203, v203, v12
	v_add_f32_e32 v205, v205, v13
	v_add_f32_e32 v203, v203, v14
	v_add_f32_e32 v205, v205, v15
	v_add_f32_e32 v203, v203, v16
	v_add_f32_e32 v205, v205, v17
	v_add_f32_e32 v203, v203, v18
	v_add_f32_e32 v205, v205, v19
	v_add_f32_e32 v203, v203, v20
	v_add_f32_e32 v205, v205, v21
	v_add_f32_e32 v203, v203, v22
	v_add_f32_e32 v205, v205, v23
	v_add_f32_e32 v203, v203, v24
	v_add_f32_e32 v205, v205, v25
	v_add_f32_e32 v203, v203, v26
	v_add_f32_e32 v205, v205, v27
	v_add_f32_e32 v203, v203, v28
	v_add_f32_e32 v205, v205, v29
	v_add_f32_e32 v203, v203, v30
	v_add_f32_e32 v205, v205, v31
	v_add_f32_e32 v203, v203, v205
	v_add_f32_e32 v201, v201, v203
	v_cvt_pk_bf16_f32 v48, v0, v1
	v_cvt_pk_bf16_f32 v49, v2, v3
	v_cvt_pk_bf16_f32 v50, v4, v5
	v_cvt_pk_bf16_f32 v51, v6, v7
	v_cvt_pk_bf16_f32 v52, v8, v9
	v_cvt_pk_bf16_f32 v53, v10, v11
	v_cvt_pk_bf16_f32 v54, v12, v13
	v_cvt_pk_bf16_f32 v55, v14, v15
	v_cvt_pk_bf16_f32 v56, v16, v17
	v_cvt_pk_bf16_f32 v57, v18, v19
	v_cvt_pk_bf16_f32 v58, v20, v21
	v_cvt_pk_bf16_f32 v59, v22, v23
	v_cvt_pk_bf16_f32 v60, v24, v25
	v_cvt_pk_bf16_f32 v61, v26, v27
	v_cvt_pk_bf16_f32 v62, v28, v29
	v_cvt_pk_bf16_f32 v63, v30, v31
	ds_read_b128 v[112:115], v146 offset:0
	ds_read_b128 v[116:119], v146 offset:4096
	ds_read_b128 v[120:123], v146 offset:8192
	ds_read_b128 v[124:127], v146 offset:12288
	ds_read_b128 v[128:131], v147 offset:0
	ds_read_b128 v[132:135], v147 offset:4096
	ds_read_b128 v[136:139], v147 offset:8192
	ds_read_b128 v[140:143], v147 offset:12288
	s_waitcnt lgkmcnt(7)
	v_mfma_f32_16x16x32_bf16 v[32:35], v[112:115], v[48:51], v[32:35]
	ds_read_b128 v[112:115], v148 offset:0
	s_waitcnt lgkmcnt(7)
	v_mfma_f32_16x16x32_bf16 v[36:39], v[116:119], v[48:51], v[36:39]
	ds_read_b128 v[116:119], v148 offset:4096
	s_waitcnt lgkmcnt(7)
	v_mfma_f32_16x16x32_bf16 v[40:43], v[120:123], v[48:51], v[40:43]
	ds_read_b128 v[120:123], v148 offset:8192
	s_waitcnt lgkmcnt(7)
	v_mfma_f32_16x16x32_bf16 v[44:47], v[124:127], v[48:51], v[44:47]
	ds_read_b128 v[124:127], v148 offset:12288
	s_waitcnt lgkmcnt(7)
	v_mfma_f32_16x16x32_bf16 v[32:35], v[128:131], v[52:55], v[32:35]
	ds_read_b128 v[128:131], v149 offset:0
	s_waitcnt lgkmcnt(7)
	v_mfma_f32_16x16x32_bf16 v[36:39], v[132:135], v[52:55], v[36:39]
	ds_read_b128 v[132:135], v149 offset:4096
	s_waitcnt lgkmcnt(7)
	v_mfma_f32_16x16x32_bf16 v[40:43], v[136:139], v[52:55], v[40:43]
	ds_read_b128 v[136:139], v149 offset:8192
	s_waitcnt lgkmcnt(7)
	v_mfma_f32_16x16x32_bf16 v[44:47], v[140:143], v[52:55], v[44:47]
	ds_read_b128 v[140:143], v149 offset:12288
	s_waitcnt lgkmcnt(7)
	v_mfma_f32_16x16x32_bf16 v[32:35], v[112:115], v[56:59], v[32:35]
	s_waitcnt lgkmcnt(6)
	v_mfma_f32_16x16x32_bf16 v[36:39], v[116:119], v[56:59], v[36:39]
	s_waitcnt lgkmcnt(5)
	v_mfma_f32_16x16x32_bf16 v[40:43], v[120:123], v[56:59], v[40:43]
	s_waitcnt lgkmcnt(4)
	v_mfma_f32_16x16x32_bf16 v[44:47], v[124:127], v[56:59], v[44:47]
	s_waitcnt lgkmcnt(3)
	v_mfma_f32_16x16x32_bf16 v[32:35], v[128:131], v[60:63], v[32:35]
	s_waitcnt lgkmcnt(2)
	v_mfma_f32_16x16x32_bf16 v[36:39], v[132:135], v[60:63], v[36:39]
	s_waitcnt lgkmcnt(1)
	v_mfma_f32_16x16x32_bf16 v[40:43], v[136:139], v[60:63], v[40:43]
	s_waitcnt lgkmcnt(0)
	v_mfma_f32_16x16x32_bf16 v[44:47], v[140:143], v[60:63], v[44:47]
	s_waitcnt lgkmcnt(0)
	s_barrier
; __device__ __forceinline__ void attn_phase(const Params& P, char* smem_raw) {
;     ...
;     for (int ck = 0; ck < 6; ++ck) {
;       int lane_c = lane;
;       asm volatile("" : "+v"(lane_c));
;       __syncthreads();
; #pragma unroll
;       for (int i = 0; i < 4; ++i) {
;         const int idx = tid + 256 * i;
;         *reinterpret_cast<uint4*>(&sm_k[(idx >> 3) * LDSS + (idx & 7) * 8]) = kreg[i];
;         *reinterpret_cast<uint4*>(&sm_vt[(idx >> 4) * 136 + (idx & 15) * 8]) = vreg[i];
;       }
;       __syncthreads();
;       f32x4 sacc[8];
; #pragma unroll
;       for (int t8 = 0; t8 < 8; ++t8) sacc[t8] = f32x4{0.f, 0.f, 0.f, 0.f};
; #pragma unroll
;       for (int s = 0; s < 2; ++s)
; #pragma unroll
;         for (int t8 = 0; t8 < 8; ++t8) {
;           const bf16x8 kf = *reinterpret_cast<const bf16x8*>(&sm_k[(t8 * 16 + (lane_c & 15)) * LDSS + s * 32 + (lane_c >> 4) * 8]);
;           sacc[t8] = __builtin_amdgcn_mfma_f32_16x16x32_bf16(qf[s], kf, sacc[t8], 0, 0, 0);
;         }
;       if (ck < 5) {
;         ATT_ISSUE(t, ck + 1)
;       } else if (t + VGRID < 8192) {
;         ATT_ISSUE(t + VGRID, 0)
;         ATT_QLOAD(t + VGRID)
;       }
;       if (ck < 4) {
;         const float* rb0 = sm_rpb + (rs + ck * 2 - r + 7) * 31;
; #pragma unroll
;         for (int t8 = 0; t8 < 8; ++t8)
; #pragma unroll
;           for (int reg = 0; reg < 4; ++reg)
;             sacc[t8][reg] += rb0[(t8 >> 2) * 31 + dco[reg][t8 & 3]];
;       }
; #pragma unroll
;       for (int reg = 0; reg < 4; ++reg) {
;         float mx = sacc[0][reg];
; #pragma unroll
;         for (int t8 = 1; t8 < 8; ++t8) mx = fmaxf(mx, sacc[t8][reg]);
;         mx = row16_max(mx);
;         const float mnew = fmaxf(mrow[reg], mx);
;         const float alpha = __builtin_amdgcn_exp2f(mrow[reg] - mnew);
;         mrow[reg] = mnew;
;         float rsum = 0.f;
; #pragma unroll
;         for (int t8 = 0; t8 < 8; ++t8) {
;           const float p = __builtin_amdgcn_exp2f(sacc[t8][reg] - mnew);
;           rsum += p;
;           sm_p[(wid * 16 + (lane_c >> 4) * 4 + reg) * 136 + t8 * 16 + (lane_c & 15)] = f2bf(p);
;         }
;         rsum = row16_sum(rsum);
;         lrow[reg] = lrow[reg] * alpha + rsum;
; #pragma unroll
;         for (int td = 0; td < 4; ++td) o[td][reg] *= alpha;
;       }
	s_waitcnt vmcnt(0)
	ds_write_b128 v150, v[80:83] offset:0
	ds_write_b128 v150, v[84:87] offset:4096
	ds_write_b128 v150, v[88:91] offset:8192
	ds_write_b128 v150, v[92:95] offset:12288
	ds_write_b128 v151, v[96:99] offset:0
	ds_write_b128 v151, v[100:103] offset:4096
	ds_write_b128 v151, v[104:107] offset:8192
	ds_write_b128 v151, v[108:111] offset:12288
	s_add_u32 s100, s12, 0xc0000
	s_addc_u32 s101, s13, 0
	s_add_u32 s0, s14, 0x100
	s_addc_u32 s1, s15, 0
	global_load_dwordx4 v[80:83], v154, s[100:101] offset:2048
	global_load_dwordx4 v[96:99], v158, s[0:1]
	global_load_dwordx4 v[84:87], v155, s[100:101] offset:2048
	global_load_dwordx4 v[100:103], v159, s[0:1]
	global_load_dwordx4 v[88:91], v156, s[100:101] offset:2048
	global_load_dwordx4 v[104:107], v160, s[0:1]
	global_load_dwordx4 v[92:95], v157, s[100:101] offset:2048
	global_load_dwordx4 v[108:111], v161, s[0:1]
	ds_read_b128 v[112:115], v144 offset:32768
	ds_read_b128 v[116:119], v145 offset:32768
	ds_read_b128 v[120:123], v144 offset:33280
	ds_read_b128 v[124:127], v145 offset:33280
	ds_read_b128 v[128:131], v144 offset:36864
	ds_read_b128 v[132:135], v145 offset:36864
	ds_read_b128 v[136:139], v144 offset:37376
	ds_read_b128 v[140:143], v145 offset:37376
	s_waitcnt lgkmcnt(7)
	v_mfma_f32_16x16x32_bf16 v[0:3], v[112:115], v[64:67], 0
	ds_read_b128 v[112:115], v144 offset:40960
	s_waitcnt lgkmcnt(7)
	v_mfma_f32_16x16x32_bf16 v[0:3], v[116:119], v[68:71], v[0:3]
	ds_read_b128 v[116:119], v145 offset:40960
	s_waitcnt lgkmcnt(7)
	v_mfma_f32_16x16x32_bf16 v[4:7], v[120:123], v[64:67], 0
	ds_read_b128 v[120:123], v144 offset:41472
	s_waitcnt lgkmcnt(7)
	v_mfma_f32_16x16x32_bf16 v[4:7], v[124:127], v[68:71], v[4:7]
	ds_read_b128 v[124:127], v145 offset:41472
	s_waitcnt lgkmcnt(7)
	v_mfma_f32_16x16x32_bf16 v[8:11], v[128:131], v[64:67], 0
	ds_read_b128 v[128:131], v144 offset:45056
	s_waitcnt lgkmcnt(7)
	v_mfma_f32_16x16x32_bf16 v[8:11], v[132:135], v[68:71], v[8:11]
	ds_read_b128 v[132:135], v145 offset:45056
	s_waitcnt lgkmcnt(7)
	v_mfma_f32_16x16x32_bf16 v[12:15], v[136:139], v[64:67], 0
	ds_read_b128 v[136:139], v144 offset:45568
	s_waitcnt lgkmcnt(7)
	v_mfma_f32_16x16x32_bf16 v[12:15], v[140:143], v[68:71], v[12:15]
	ds_read_b128 v[140:143], v145 offset:45568
	s_waitcnt lgkmcnt(7)
	v_mfma_f32_16x16x32_bf16 v[16:19], v[112:115], v[64:67], 0
	s_waitcnt lgkmcnt(6)
	v_mfma_f32_16x16x32_bf16 v[16:19], v[116:119], v[68:71], v[16:19]
	s_waitcnt lgkmcnt(5)
	v_mfma_f32_16x16x32_bf16 v[20:23], v[120:123], v[64:67], 0
	s_waitcnt lgkmcnt(4)
	v_mfma_f32_16x16x32_bf16 v[20:23], v[124:127], v[68:71], v[20:23]
	s_waitcnt lgkmcnt(3)
	v_mfma_f32_16x16x32_bf16 v[24:27], v[128:131], v[64:67], 0
	s_waitcnt lgkmcnt(2)
	v_mfma_f32_16x16x32_bf16 v[24:27], v[132:135], v[68:71], v[24:27]
	s_waitcnt lgkmcnt(1)
	v_mfma_f32_16x16x32_bf16 v[28:31], v[136:139], v[64:67], 0
	s_waitcnt lgkmcnt(0)
	v_mfma_f32_16x16x32_bf16 v[28:31], v[140:143], v[68:71], v[28:31]
	s_nop 7
	v_max3_f32 v203, v0, v1, v2
	v_max3_f32 v203, v203, v3, v4
	v_max3_f32 v203, v203, v5, v6
	v_max3_f32 v203, v203, v7, v8
	v_max3_f32 v203, v203, v9, v10
	v_max3_f32 v203, v203, v11, v12
	v_max3_f32 v203, v203, v13, v14
	v_max3_f32 v203, v203, v15, v16
	v_max3_f32 v203, v203, v17, v18
	v_max3_f32 v203, v203, v19, v20
	v_max3_f32 v203, v203, v21, v22
	v_max3_f32 v203, v203, v23, v24
	v_max3_f32 v203, v203, v25, v26
	v_max3_f32 v203, v203, v27, v28
	v_max3_f32 v203, v203, v29, v30
	v_max_f32_e32 v203, v203, v31
	v_mov_b32_e32 v205, v203
	s_nop 1
	v_permlane16_swap_b32_e32 v203, v205
	v_max_f32_e32 v203, v203, v205
	v_mov_b32_e32 v205, v203
	s_nop 1
	v_permlane32_swap_b32_e32 v203, v205
	v_max_f32_e32 v203, v203, v205
	v_max_f32_e32 v208, v200, v203
	v_sub_f32_e32 v202, v200, v208
	v_exp_f32_e32 v202, v202
	v_mov_b32_e32 v200, v208
	v_sub_f32_e32 v0, v0, v208
	v_sub_f32_e32 v1, v1, v208
	v_sub_f32_e32 v2, v2, v208
	v_sub_f32_e32 v3, v3, v208
	v_sub_f32_e32 v4, v4, v208
	v_sub_f32_e32 v5, v5, v208
	v_sub_f32_e32 v6, v6, v208
	v_sub_f32_e32 v7, v7, v208
	v_sub_f32_e32 v8, v8, v208
	v_sub_f32_e32 v9, v9, v208
	v_sub_f32_e32 v10, v10, v208
	v_sub_f32_e32 v11, v11, v208
	v_sub_f32_e32 v12, v12, v208
	v_sub_f32_e32 v13, v13, v208
	v_sub_f32_e32 v14, v14, v208
	v_sub_f32_e32 v15, v15, v208
	v_sub_f32_e32 v16, v16, v208
	v_sub_f32_e32 v17, v17, v208
	v_sub_f32_e32 v18, v18, v208
	v_sub_f32_e32 v19, v19, v208
	v_sub_f32_e32 v20, v20, v208
	v_sub_f32_e32 v21, v21, v208
	v_sub_f32_e32 v22, v22, v208
	v_sub_f32_e32 v23, v23, v208
	v_sub_f32_e32 v24, v24, v208
	v_sub_f32_e32 v25, v25, v208
	v_sub_f32_e32 v26, v26, v208
	v_sub_f32_e32 v27, v27, v208
	v_sub_f32_e32 v28, v28, v208
	v_sub_f32_e32 v29, v29, v208
	v_sub_f32_e32 v30, v30, v208
	v_sub_f32_e32 v31, v31, v208
	v_exp_f32_e32 v0, v0
	v_exp_f32_e32 v1, v1
	v_exp_f32_e32 v2, v2
	v_exp_f32_e32 v3, v3
	v_exp_f32_e32 v4, v4
	v_exp_f32_e32 v5, v5
	v_exp_f32_e32 v6, v6
	v_exp_f32_e32 v7, v7
	v_exp_f32_e32 v8, v8
	v_exp_f32_e32 v9, v9
	v_exp_f32_e32 v10, v10
	v_exp_f32_e32 v11, v11
	v_exp_f32_e32 v12, v12
	v_exp_f32_e32 v13, v13
	v_exp_f32_e32 v14, v14
	v_exp_f32_e32 v15, v15
	v_exp_f32_e32 v16, v16
	v_exp_f32_e32 v17, v17
	v_exp_f32_e32 v18, v18
	v_exp_f32_e32 v19, v19
	v_exp_f32_e32 v20, v20
	v_exp_f32_e32 v21, v21
	v_exp_f32_e32 v22, v22
	v_exp_f32_e32 v23, v23
	v_exp_f32_e32 v24, v24
	v_exp_f32_e32 v25, v25
	v_exp_f32_e32 v26, v26
	v_exp_f32_e32 v27, v27
	v_exp_f32_e32 v28, v28
	v_exp_f32_e32 v29, v29
	v_exp_f32_e32 v30, v30
	v_exp_f32_e32 v31, v31
	v_mul_f32_e32 v201, v201, v202
	v_mul_f32_e32 v32, v32, v202
	v_mul_f32_e32 v33, v33, v202
	v_mul_f32_e32 v34, v34, v202
	v_mul_f32_e32 v35, v35, v202
; __device__ __forceinline__ void attn_phase(const Params& P, char* smem_raw) {
;     ...
; #pragma unroll
;       for (int s4 = 0; s4 < 4; ++s4) {
;         const bf16x8 pf = *reinterpret_cast<const bf16x8*>(&sm_p[(wid * 16 + (lane_c & 15)) * 136 + s4 * 32 + (lane_c >> 4) * 8]);
; #pragma unroll
;         for (int td = 0; td < 4; ++td) {
;           const bf16x8 vf = *reinterpret_cast<const bf16x8*>(&sm_vt[(td * 16 + (lane_c & 15)) * 136 + s4 * 32 + (lane_c >> 4) * 8]);
;           o[td] = __builtin_amdgcn_mfma_f32_16x16x32_bf16(pf, vf, o[td], 0, 0, 0);
;         }
;       }
;     }
;     u16* Ob = P.cat + ((long)b * 8192 + r * 64) * 1024 + h * 64;
; #pragma unroll
;     for (int td = 0; td < 4; ++td)
; #pragma unroll
;       for (int reg = 0; reg < 4; ++reg) {
;         const int rowl = wid * 16 + (lane >> 4) * 4 + reg;
;         Ob[(unsigned)(rowl * 1024 + td * 16 + (lane & 15))] = f2bf(o[td][reg] * __builtin_amdgcn_rcpf(lrow[reg]));
;       }
;   }
	v_mul_f32_e32 v36, v36, v202
	v_mul_f32_e32 v37, v37, v202
	v_mul_f32_e32 v38, v38, v202
	v_mul_f32_e32 v39, v39, v202
	v_mul_f32_e32 v40, v40, v202
	v_mul_f32_e32 v41, v41, v202
	v_mul_f32_e32 v42, v42, v202
	v_mul_f32_e32 v43, v43, v202
	v_mul_f32_e32 v44, v44, v202
	v_mul_f32_e32 v45, v45, v202
	v_mul_f32_e32 v46, v46, v202
	v_mul_f32_e32 v47, v47, v202
	v_add_f32_e32 v203, v0, v1
	v_add_f32_e32 v205, v2, v3
	v_add_f32_e32 v203, v203, v4
	v_add_f32_e32 v205, v205, v5
	v_add_f32_e32 v203, v203, v6
	v_add_f32_e32 v205, v205, v7
	v_add_f32_e32 v203, v203, v8
	v_add_f32_e32 v205, v205, v9
	v_add_f32_e32 v203, v203, v10
	v_add_f32_e32 v205, v205, v11
	v_add_f32_e32 v203, v203, v12
	v_add_f32_e32 v205, v205, v13
	v_add_f32_e32 v203, v203, v14
	v_add_f32_e32 v205, v205, v15
	v_add_f32_e32 v203, v203, v16
	v_add_f32_e32 v205, v205, v17
	v_add_f32_e32 v203, v203, v18
	v_add_f32_e32 v205, v205, v19
	v_add_f32_e32 v203, v203, v20
	v_add_f32_e32 v205, v205, v21
	v_add_f32_e32 v203, v203, v22
	v_add_f32_e32 v205, v205, v23
	v_add_f32_e32 v203, v203, v24
	v_add_f32_e32 v205, v205, v25
	v_add_f32_e32 v203, v203, v26
	v_add_f32_e32 v205, v205, v27
	v_add_f32_e32 v203, v203, v28
	v_add_f32_e32 v205, v205, v29
	v_add_f32_e32 v203, v203, v30
	v_add_f32_e32 v205, v205, v31
	v_add_f32_e32 v203, v203, v205
	v_add_f32_e32 v201, v201, v203
	v_cvt_pk_bf16_f32 v48, v0, v1
	v_cvt_pk_bf16_f32 v49, v2, v3
	v_cvt_pk_bf16_f32 v50, v4, v5
	v_cvt_pk_bf16_f32 v51, v6, v7
	v_cvt_pk_bf16_f32 v52, v8, v9
	v_cvt_pk_bf16_f32 v53, v10, v11
	v_cvt_pk_bf16_f32 v54, v12, v13
	v_cvt_pk_bf16_f32 v55, v14, v15
	v_cvt_pk_bf16_f32 v56, v16, v17
	v_cvt_pk_bf16_f32 v57, v18, v19
	v_cvt_pk_bf16_f32 v58, v20, v21
	v_cvt_pk_bf16_f32 v59, v22, v23
	v_cvt_pk_bf16_f32 v60, v24, v25
	v_cvt_pk_bf16_f32 v61, v26, v27
	v_cvt_pk_bf16_f32 v62, v28, v29
	v_cvt_pk_bf16_f32 v63, v30, v31
	ds_read_b128 v[112:115], v146 offset:32768
	ds_read_b128 v[116:119], v146 offset:36864
	ds_read_b128 v[120:123], v146 offset:40960
	ds_read_b128 v[124:127], v146 offset:45056
	ds_read_b128 v[128:131], v147 offset:32768
	ds_read_b128 v[132:135], v147 offset:36864
	ds_read_b128 v[136:139], v147 offset:40960
	ds_read_b128 v[140:143], v147 offset:45056
	s_waitcnt lgkmcnt(7)
	v_mfma_f32_16x16x32_bf16 v[32:35], v[112:115], v[48:51], v[32:35]
	ds_read_b128 v[112:115], v148 offset:32768
	s_waitcnt lgkmcnt(7)
	v_mfma_f32_16x16x32_bf16 v[36:39], v[116:119], v[48:51], v[36:39]
	ds_read_b128 v[116:119], v148 offset:36864
	s_waitcnt lgkmcnt(7)
	v_mfma_f32_16x16x32_bf16 v[40:43], v[120:123], v[48:51], v[40:43]
	ds_read_b128 v[120:123], v148 offset:40960
	s_waitcnt lgkmcnt(7)
	v_mfma_f32_16x16x32_bf16 v[44:47], v[124:127], v[48:51], v[44:47]
	ds_read_b128 v[124:127], v148 offset:45056
	s_waitcnt lgkmcnt(7)
	v_mfma_f32_16x16x32_bf16 v[32:35], v[128:131], v[52:55], v[32:35]
	ds_read_b128 v[128:131], v149 offset:32768
	s_waitcnt lgkmcnt(7)
	v_mfma_f32_16x16x32_bf16 v[36:39], v[132:135], v[52:55], v[36:39]
	ds_read_b128 v[132:135], v149 offset:36864
	s_waitcnt lgkmcnt(7)
	v_mfma_f32_16x16x32_bf16 v[40:43], v[136:139], v[52:55], v[40:43]
	ds_read_b128 v[136:139], v149 offset:40960
	s_waitcnt lgkmcnt(7)
	v_mfma_f32_16x16x32_bf16 v[44:47], v[140:143], v[52:55], v[44:47]
	ds_read_b128 v[140:143], v149 offset:45056
	s_waitcnt lgkmcnt(7)
	v_mfma_f32_16x16x32_bf16 v[32:35], v[112:115], v[56:59], v[32:35]
	s_waitcnt lgkmcnt(6)
	v_mfma_f32_16x16x32_bf16 v[36:39], v[116:119], v[56:59], v[36:39]
	s_waitcnt lgkmcnt(5)
	v_mfma_f32_16x16x32_bf16 v[40:43], v[120:123], v[56:59], v[40:43]
	s_waitcnt lgkmcnt(4)
	v_mfma_f32_16x16x32_bf16 v[44:47], v[124:127], v[56:59], v[44:47]
	s_waitcnt lgkmcnt(3)
	v_mfma_f32_16x16x32_bf16 v[32:35], v[128:131], v[60:63], v[32:35]
	s_waitcnt lgkmcnt(2)
	v_mfma_f32_16x16x32_bf16 v[36:39], v[132:135], v[60:63], v[36:39]
	s_waitcnt lgkmcnt(1)
	v_mfma_f32_16x16x32_bf16 v[40:43], v[136:139], v[60:63], v[40:43]
	s_waitcnt lgkmcnt(0)
	v_mfma_f32_16x16x32_bf16 v[44:47], v[140:143], v[60:63], v[44:47]
	ds_read_b32 v0, v184 offset:384
	ds_read_b32 v1, v185 offset:384
	ds_read_b32 v2, v186 offset:384
	ds_read_b32 v3, v187 offset:384
	ds_read_b32 v4, v188 offset:384
	ds_read_b32 v5, v189 offset:384
	ds_read_b32 v6, v190 offset:384
	ds_read_b32 v7, v191 offset:384
	ds_read_b32 v8, v192 offset:384
	ds_read_b32 v9, v193 offset:384
	ds_read_b32 v10, v194 offset:384
	ds_read_b32 v11, v195 offset:384
	ds_read_b32 v12, v196 offset:384
	ds_read_b32 v13, v197 offset:384
	ds_read_b32 v14, v198 offset:384
	ds_read_b32 v15, v199 offset:384
	ds_read_b32 v16, v184 offset:512
	ds_read_b32 v17, v185 offset:512
	ds_read_b32 v18, v186 offset:512
	ds_read_b32 v19, v187 offset:512
	ds_read_b32 v20, v188 offset:512
	ds_read_b32 v21, v189 offset:512
	ds_read_b32 v22, v190 offset:512
	ds_read_b32 v23, v191 offset:512
	ds_read_b32 v24, v192 offset:512
	ds_read_b32 v25, v193 offset:512
	ds_read_b32 v26, v194 offset:512
	ds_read_b32 v27, v195 offset:512
	ds_read_b32 v28, v196 offset:512
	ds_read_b32 v29, v197 offset:512
	ds_read_b32 v30, v198 offset:512
	ds_read_b32 v31, v199 offset:512
	s_waitcnt lgkmcnt(0)
	v_mov_b32_e32 v205, v201
	s_nop 1
	v_permlane16_swap_b32_e32 v201, v205
	v_add_f32_e32 v201, v201, v205
	v_mov_b32_e32 v205, v201
	s_nop 1
	v_permlane32_swap_b32_e32 v201, v205
	v_add_f32_e32 v201, v201, v205
	v_rcp_f32_e32 v203, v201
	s_nop 7
	v_mul_f32_e32 v32, v32, v203
	v_mul_f32_e32 v33, v33, v203
	v_mul_f32_e32 v34, v34, v203
	v_mul_f32_e32 v35, v35, v203
	v_mul_f32_e32 v36, v36, v203
	v_mul_f32_e32 v37, v37, v203
	v_mul_f32_e32 v38, v38, v203
	v_mul_f32_e32 v39, v39, v203
	v_mul_f32_e32 v40, v40, v203
	v_mul_f32_e32 v41, v41, v203
	v_mul_f32_e32 v42, v42, v203
	v_mul_f32_e32 v43, v43, v203
	v_mul_f32_e32 v44, v44, v203
	v_mul_f32_e32 v45, v45, v203
	v_mul_f32_e32 v46, v46, v203
	v_mul_f32_e32 v47, v47, v203
	v_cvt_pk_bf16_f32 v210, v32, v33
	v_cvt_pk_bf16_f32 v211, v34, v35
	v_cvt_pk_bf16_f32 v212, v36, v37
	v_cvt_pk_bf16_f32 v213, v38, v39
	v_cvt_pk_bf16_f32 v214, v40, v41
	v_cvt_pk_bf16_f32 v215, v42, v43
	v_cvt_pk_bf16_f32 v216, v44, v45
	v_cvt_pk_bf16_f32 v217, v46, v47
	global_store_dwordx2 v167, v[210:211], s[98:99] offset:0
	global_store_dwordx2 v167, v[212:213], s[98:99] offset:32
	global_store_dwordx2 v167, v[214:215], s[98:99] offset:64
	global_store_dwordx2 v167, v[216:217], s[98:99] offset:96
	v_mov_b32_e32 v200, 0xf149f2ca
	v_mov_b32_e32 v201, 0
	v_mov_b32_e32 v32, 0
	v_mov_b32_e32 v33, 0
	v_mov_b32_e32 v34, 0
	v_mov_b32_e32 v35, 0
	v_mov_b32_e32 v36, 0
	v_mov_b32_e32 v37, 0
	v_mov_b32_e32 v38, 0
	v_mov_b32_e32 v39, 0
	v_mov_b32_e32 v40, 0
	v_mov_b32_e32 v41, 0
	v_mov_b32_e32 v42, 0
	v_mov_b32_e32 v43, 0
	v_mov_b32_e32 v44, 0
	v_mov_b32_e32 v45, 0
	v_mov_b32_e32 v46, 0
	v_mov_b32_e32 v47, 0
	v_mov_b32_e32 v64, v72
	v_mov_b32_e32 v65, v73
	v_mov_b32_e32 v66, v74
	v_mov_b32_e32 v67, v75
	v_mov_b32_e32 v68, v76
	v_mov_b32_e32 v69, v77
	v_mov_b32_e32 v70, v78
	v_mov_b32_e32 v71, v79
	s_add_u32 s3, s3, 1
	s_and_b32 s0, s3, 0xff
	s_cmp_lt_u32 s0, 16
	s_cbranch_scc1 .Lmy_att_tile
; __device__ __forceinline__ void attn_phase(const Params& P, char* smem_raw) {
;     ...
;       }
;   }
;     ...
; }
	s_waitcnt vmcnt(0)
	s_branch .LBB0_1501
